# w13 next-tile prefetch, fin gn_store load batching, L1/L2 look-ahead bursts in hyena short-conv and adaLN GEMV
# speedup vs baseline: 1.0813x; 1.0189x over previous
.LBB0_114:
	v_add_u32_e32 v7, 0x100, v7
	s_movk_i32 s20, 0x5df
	v_cmp_lt_u32_e64 s[42:43], s20, v7
	ds_write_b128 v6, v[210:213]
	s_or_b64 s[0:1], s[42:43], s[0:1]
	v_add_u32_e32 v6, 0x1000, v6
	s_andn2_b64 exec, exec, s[0:1]
	s_cbranch_execnz .LBB0_114
	s_or_b64 exec, exec, s[0:1]
	s_add_i32 s30, s26, 0x400
	s_lshl_b64 s[20:21], s[30:31], 2
	s_add_u32 s0, s89, s20
	s_addc_u32 s1, s90, s21
	s_waitcnt lgkmcnt(0)
	s_barrier
	global_load_dword v15, v1, s[0:1]
	s_lshl_b64 s[0:1], s[28:29], 2
	s_add_u32 s22, s89, s0
	s_addc_u32 s23, s90, s1
	s_add_u32 s20, s91, s20
	v_mov_b32_e32 v6, 0x5000
	v_mov_b32_e32 v7, 0x8000
	s_addc_u32 s21, s92, s21
	global_load_dword v6, v6, s[22:23]
	s_movk_i32 s4, 0xff
	global_load_dword v7, v7, s[22:23]
	v_cmp_ne_u32_e64 s[42:43], s4, v3
	global_load_dword v16, v1, s[20:21]
	v_readlane_b32 s4, v254, 23
	s_lshl_b64 s[20:21], s[30:31], 14
	v_readlane_b32 s6, v254, 25
	s_waitcnt vmcnt(6)
	v_lshrrev_b32_e32 v8, 5, v3
	s_waitcnt vmcnt(21)
	v_and_b32_e32 v9, 31, v14
	v_readlane_b32 s7, v254, 26
	s_add_u32 s20, s6, s20
	v_mul_u32_u24_e32 v8, 0x50, v8
	v_lshlrev_b32_e32 v9, 1, v9
	s_addc_u32 s21, s7, s21
	s_waitcnt vmcnt(15)
	v_add3_u32 v17, v8, v9, s54
	v_lshl_add_u64 v[8:9], s[20:21], 0, v[0:1]
	s_mov_b64 s[20:21], 0
	v_readlane_b32 s5, v254, 24
	s_mov_b64 s[22:23], 0x1000
	v_lshl_add_u64 v[244:245], v[8:9], 0, s[22:23]
	global_load_ushort v214, v[8:9], off
	global_load_ushort v215, v[8:9], off offset:512
	global_load_ushort v216, v[8:9], off offset:1024
	global_load_ushort v217, v[8:9], off offset:1536
	global_load_ushort v218, v[8:9], off offset:2048
	global_load_ushort v219, v[8:9], off offset:2560
	global_load_ushort v220, v[8:9], off offset:3072
	global_load_ushort v221, v[8:9], off offset:3584
	global_load_ushort v236, v[244:245], off
	global_load_ushort v237, v[244:245], off offset:512
	global_load_ushort v238, v[244:245], off offset:1024
	global_load_ushort v239, v[244:245], off offset:1536
	global_load_ushort v240, v[244:245], off offset:2048
	global_load_ushort v241, v[244:245], off offset:2560
	global_load_ushort v242, v[244:245], off offset:3072
	global_load_ushort v243, v[244:245], off offset:3584
	s_branch .LBB0_117

.LBB0_244:
	v_add_u32_e32 v7, 0x100, v7
	s_movk_i32 s20, 0x66b
	v_cmp_lt_u32_e32 vcc, s20, v7
	ds_write_b128 v0, v[210:213]
	s_or_b64 s[0:1], vcc, s[0:1]
	v_add_u32_e32 v0, 0x1000, v0
	s_andn2_b64 exec, exec, s[0:1]
	s_cbranch_execnz .LBB0_244
	s_or_b64 exec, exec, s[0:1]
	s_add_i32 s20, s26, 0x800
	s_ashr_i32 s21, s20, 31
	s_lshl_b64 s[22:23], s[20:21], 2
	s_add_u32 s42, s89, s22
	s_addc_u32 s43, s90, s23
	s_lshl_b64 s[0:1], s[26:27], 2
	s_add_u32 s28, s89, s0
	s_addc_u32 s29, s90, s1
	s_add_u32 s22, s91, s22
	v_mov_b32_e32 v0, 0x5000
	s_waitcnt lgkmcnt(0)
	s_barrier
	s_addc_u32 s23, s92, s23
	global_load_dword v34, v1, s[42:43]
	global_load_dword v9, v0, s[28:29]
	global_load_dword v11, v1, s[22:23]
	v_mov_b32_e32 v0, 0x8000
	global_load_dword v35, v0, s[28:29]
	s_ashr_i32 s21, s51, 31
	s_ashr_i32 s23, s24, 31
	s_add_u32 s22, s51, s24
	s_addc_u32 s23, s21, s23
	v_mov_b64_e32 v[36:37], 0x7ff
	v_cmp_lt_i64_e32 vcc, s[22:23], v[36:37]
	s_and_b64 s[24:25], vcc, exec
	s_cselect_b32 s23, s23, 0
	s_cselect_b32 s22, s22, 0x7ff
	v_readlane_b32 s4, v254, 23
	s_lshl_b64 s[22:23], s[22:23], 14
	v_readlane_b32 s6, v254, 25
	v_readlane_b32 s7, v254, 26
	s_add_u32 s22, s6, s22
	v_lshlrev_b32_e32 v0, 1, v3
	s_addc_u32 s23, s7, s23
	v_and_b32_e32 v7, 31, v5
	v_lshl_add_u64 v[36:37], s[22:23], 0, v[0:1]
	v_or_b32_e32 v0, 0x200, v3
	v_or_b32_e32 v15, 0x100, v3
	v_lshl_add_u32 v13, v7, 1, s33
	s_mov_b32 s21, 0
	v_lshrrev_b32_e32 v0, 5, v0
	v_lshrrev_b32_e32 v15, 5, v15
	s_mov_b64 s[22:23], 0
	v_mov_b32_e32 v17, v3
	v_readlane_b32 s5, v254, 24
	v_add_co_u32_e32 v244, vcc, 0x2002000, v36
	s_nop 1
	v_addc_co_u32_e32 v245, vcc, 0, v37, vcc
	v_add_co_u32_e32 v246, vcc, 0x1000, v244
	s_nop 1
	v_addc_co_u32_e32 v247, vcc, 0, v245, vcc
	global_load_dword v214, v[244:245], off
	global_load_dword v215, v[244:245], off offset:512
	global_load_dword v216, v[244:245], off offset:1024
	global_load_dword v217, v[244:245], off offset:1536
	global_load_dword v218, v[244:245], off offset:2048
	global_load_dword v219, v[244:245], off offset:2560
	global_load_dword v220, v[244:245], off offset:3072
	global_load_dword v221, v[244:245], off offset:3584
	global_load_dword v236, v[246:247], off
	global_load_dword v237, v[246:247], off offset:512
	global_load_dword v238, v[246:247], off offset:1024
	global_load_dword v239, v[246:247], off offset:1536
	global_load_dword v240, v[246:247], off offset:2048
	global_load_dword v241, v[246:247], off offset:2560
	global_load_dword v242, v[246:247], off offset:3072
	global_load_dword v243, v[246:247], off offset:3584
	s_branch .LBB0_247

.LBB0_257:
	s_add_i32 s46, s23, s26
	s_ashr_i32 s47, s46, 31
	v_readlane_b32 s4, v254, 23
	s_lshl_b64 s[0:1], s[46:47], 14
	v_readlane_b32 s6, v254, 25
	v_readlane_b32 s7, v254, 26
	s_add_u32 s0, s6, s0
	s_addc_u32 s1, s7, s1
	v_mov_b32_e32 v109, v1
	v_lshl_add_u64 v[2:3], s[0:1], 0, v[108:109]
	s_mov_b64 s[0:1], 0x2000
	v_lshl_add_u64 v[2:3], v[2:3], 0, s[0:1]
	v_mov_b32_e32 v109, 0
	v_mov_b32_e32 v182, 0
	v_readlane_b32 s5, v254, 24
	s_and_saveexec_b64 s[0:1], s[42:43]
	s_cbranch_execz .LBB0_259
	v_lshl_add_u64 v[4:5], v[42:43], 1, v[2:3]
	global_load_ushort v182, v[4:5], off
.LBB0_259:
	s_or_b64 exec, exec, s[0:1]
	v_lshl_add_u64 v[4:5], v[2:3], 0, v[0:1]
	global_load_dwordx2 v[114:115], v[4:5], off
	global_load_ushort v181, v[4:5], off offset:8
	global_load_dwordx3 v[38:40], v[4:5], off offset:14
	global_load_dwordx3 v[34:36], v[4:5], off offset:30
	global_load_dwordx2 v[112:113], v[4:5], off offset:46
	global_load_ushort v180, v[4:5], off offset:54
	s_and_saveexec_b64 s[0:1], s[44:45]
	s_cbranch_execz .LBB0_261
	v_mov_b32_e32 v111, v1
	v_lshl_add_u64 v[2:3], v[2:3], 0, v[110:111]
	global_load_ushort v109, v[2:3], off

.LBB0_263:
	s_mov_b32 s0, 0xffff
	s_waitcnt vmcnt(10)
	v_bfi_b32 v114, s0, v114, v114
	v_lshlrev_b32_e32 v187, 16, v114
	s_nop 3
	v_add_f32_e32 v2, v2, v18
	s_waitcnt vmcnt(2)
	v_lshlrev_b32_e32 v182, 16, v182
	v_lshlrev_b32_e32 v109, 16, v109
	v_mul_f32_e32 v18, v185, v187
	v_and_b32_e32 v114, 0xffff0000, v114
	v_fmac_f32_e32 v18, v182, v183
	s_waitcnt vmcnt(1)
	v_fmac_f32_e32 v18, v184, v114
	v_fmac_f32_e32 v2, v111, v188
	s_waitcnt vmcnt(0)
	v_add_f32_e32 v18, v186, v18
	v_mul_f32_e32 v2, v18, v2
	v_cvt_pk_bf16_f32 v18, v2, s0
	s_mov_b64 s[0:1], -1
	s_and_b64 vcc, exec, s[52:53]
	s_cbranch_vccz .LBB0_327
	global_store_short v[76:77], v18, off
	s_cbranch_execz .LBB0_328

.LBB0_484:
	s_add_i32 s0, s26, 0x1000
	v_or_b32_e32 v76, s0, v2
	v_ashrrev_i32_e32 v77, 31, v76
	v_lshlrev_b64 v[80:81], 11, v[76:77]
	v_lshlrev_b64 v[76:77], 10, v[76:77]
	v_lshl_add_u64 v[76:77], v[72:73], 0, v[76:77]
	s_waitcnt lgkmcnt(0)
	s_barrier
	global_load_dword v162, v[68:69], off
	global_load_dword v161, v[70:71], off
	v_readlane_b32 s6, v253, 38
	v_readlane_b32 s7, v253, 39
	s_nop 4
	v_or_b32_e32 v240, s0, v2
	v_lshlrev_b32_e32 v241, 11, v240
	v_add_u32_e32 v241, v241, v0
	v_lshlrev_b32_e32 v244, 10, v240
	v_mov_b32_e32 v245, 0
	v_lshl_add_u64 v[244:245], v[72:73], 0, v[244:245]
	global_load_ushort v170, v[244:245], off
	global_load_dword v171, v241, s[6:7]
	v_or_b32_e32 v240, s0, v11
	v_lshlrev_b32_e32 v242, 11, v240
	v_add_u32_e32 v242, v242, v0
	v_lshlrev_b32_e32 v246, 10, v240
	v_mov_b32_e32 v247, 0
	v_lshl_add_u64 v[246:247], v[72:73], 0, v[246:247]
	global_load_dword v172, v242, s[6:7]
	v_add_u32_e32 v241, 0x1000000, v241
	v_add_u32_e32 v242, 0x1000000, v242
	global_load_dword v173, v241, s[6:7]
	global_load_dword v174, v242, s[6:7]
	global_load_ushort v175, v[246:247], off
	v_or_b32_e32 v240, s0, v15
	v_lshlrev_b32_e32 v241, 11, v240
	v_add_u32_e32 v241, v241, v0
	v_lshlrev_b32_e32 v244, 10, v240
	v_mov_b32_e32 v245, 0
	v_lshl_add_u64 v[244:245], v[72:73], 0, v[244:245]
	global_load_ushort v176, v[244:245], off
	global_load_dword v177, v241, s[6:7]
	v_or_b32_e32 v240, s0, v19
	v_lshlrev_b32_e32 v242, 11, v240
	v_add_u32_e32 v242, v242, v0
	v_lshlrev_b32_e32 v246, 10, v240
	v_mov_b32_e32 v247, 0
	v_lshl_add_u64 v[246:247], v[72:73], 0, v[246:247]
	global_load_dword v178, v242, s[6:7]
	v_add_u32_e32 v241, 0x1000000, v241
	v_add_u32_e32 v242, 0x1000000, v242
	global_load_dword v179, v241, s[6:7]
	global_load_dword v180, v242, s[6:7]
	global_load_ushort v181, v[246:247], off
	v_or_b32_e32 v240, s0, v23
	v_lshlrev_b32_e32 v241, 11, v240
	v_add_u32_e32 v241, v241, v0
	v_lshlrev_b32_e32 v244, 10, v240
	v_mov_b32_e32 v245, 0
	v_lshl_add_u64 v[244:245], v[72:73], 0, v[244:245]
	global_load_ushort v182, v[244:245], off
	global_load_dword v183, v241, s[6:7]
	v_or_b32_e32 v240, s0, v27
	v_lshlrev_b32_e32 v242, 11, v240
	v_add_u32_e32 v242, v242, v0
	v_lshlrev_b32_e32 v246, 10, v240
	v_mov_b32_e32 v247, 0
	v_lshl_add_u64 v[246:247], v[72:73], 0, v[246:247]
	global_load_dword v184, v242, s[6:7]
	v_add_u32_e32 v241, 0x1000000, v241
	v_add_u32_e32 v242, 0x1000000, v242
	global_load_dword v185, v241, s[6:7]
	global_load_dword v186, v242, s[6:7]
	global_load_ushort v187, v[246:247], off
	v_or_b32_e32 v240, s0, v31
	v_lshlrev_b32_e32 v241, 11, v240
	v_add_u32_e32 v241, v241, v0
	v_lshlrev_b32_e32 v244, 10, v240
	v_mov_b32_e32 v245, 0
	v_lshl_add_u64 v[244:245], v[72:73], 0, v[244:245]
	global_load_ushort v188, v[244:245], off
	global_load_dword v189, v241, s[6:7]
	v_or_b32_e32 v240, s0, v122
	v_lshlrev_b32_e32 v242, 11, v240
	v_add_u32_e32 v242, v242, v0
	v_lshlrev_b32_e32 v246, 10, v240
	v_mov_b32_e32 v247, 0
	v_lshl_add_u64 v[246:247], v[72:73], 0, v[246:247]
	global_load_dword v190, v242, s[6:7]
	v_add_u32_e32 v241, 0x1000000, v241
	v_add_u32_e32 v242, 0x1000000, v242
	global_load_dword v191, v241, s[6:7]
	global_load_dword v192, v242, s[6:7]
	global_load_ushort v193, v[246:247], off
	s_waitcnt vmcnt(0)
	v_or_b32_e32 v118, s0, v11
	v_mov_b32_e32 v76, v170
	v_readlane_b32 s4, v253, 36
	v_ashrrev_i32_e32 v119, 31, v118
	v_readlane_b32 s6, v253, 38
	v_readlane_b32 s7, v253, 39
	v_lshlrev_b64 v[120:121], 11, v[118:119]
	s_mov_b32 s4, 0x1000000
	v_lshl_add_u64 v[114:115], s[6:7], 0, v[80:81]
	v_lshl_add_u64 v[114:115], v[114:115], 0, v[0:1]
	v_mov_b32_e32 v117, v171
	ds_read_b32 v79, v9 offset:49408
	ds_read_b32 v78, v13 offset:49408
	v_readlane_b32 s8, v253, 40
	v_readlane_b32 s9, v253, 41
	s_mov_b32 s8, 0x3c800000
	s_mov_b32 s26, 0x3a27c5ac
	s_mov_b32 s1, 0x800000
	v_lshl_add_u64 v[80:81], v[74:75], 0, v[80:81]
	s_add_i32 s20, s20, 32
	s_cmp_ge_u32 s20, s21
	v_readlane_b32 s5, v253, 37
	v_readlane_b32 s10, v253, 42
	v_readlane_b32 s11, v253, 43
	v_lshlrev_b32_e32 v163, 16, v76
	v_lshl_add_u64 v[76:77], s[6:7], 0, v[120:121]
	v_lshl_add_u64 v[76:77], v[76:77], 0, v[0:1]
	v_mov_b32_e32 v116, v172
	v_add_co_u32_e32 v114, vcc, 0x1000000, v114
	s_waitcnt lgkmcnt(0)
	v_pk_add_f32 v[78:79], v[78:79], v[116:117]
	v_addc_co_u32_e32 v115, vcc, 0, v115, vcc
	v_add_co_u32_e32 v76, vcc, s4, v76
	v_mov_b32_e32 v115, v173
	s_nop 0
	v_addc_co_u32_e32 v77, vcc, 0, v77, vcc
	v_mov_b32_e32 v114, v174
	v_pk_add_f32 v[76:77], v[78:79], v[114:115]
	s_nop 1
	v_mov_b32_dpp v79, v77 quad_perm:[1,0,3,2] row_mask:0xf bank_mask:0xf bound_ctrl:1
	v_mov_b32_dpp v78, v76 quad_perm:[1,0,3,2] row_mask:0xf bank_mask:0xf bound_ctrl:1
	v_pk_add_f32 v[78:79], v[76:77], v[78:79]
	s_nop 1
	v_mov_b32_dpp v115, v79 quad_perm:[2,3,0,1] row_mask:0xf bank_mask:0xf bound_ctrl:1
	v_mov_b32_dpp v114, v78 quad_perm:[2,3,0,1] row_mask:0xf bank_mask:0xf bound_ctrl:1
	v_pk_add_f32 v[78:79], v[78:79], v[114:115]
	s_nop 1
	v_mov_b32_dpp v115, v79 row_half_mirror row_mask:0xf bank_mask:0xf bound_ctrl:1
	v_mov_b32_dpp v114, v78 row_half_mirror row_mask:0xf bank_mask:0xf bound_ctrl:1
	v_pk_add_f32 v[78:79], v[78:79], v[114:115]
	s_nop 1
	v_mov_b32_dpp v115, v79 row_mirror row_mask:0xf bank_mask:0xf bound_ctrl:1
	v_mov_b32_dpp v114, v78 row_mirror row_mask:0xf bank_mask:0xf bound_ctrl:1
	v_pk_add_f32 v[78:79], v[78:79], v[114:115]
	ds_bpermute_b32 v115, v159, v79
	ds_bpermute_b32 v114, v159, v78
	s_waitcnt lgkmcnt(0)
	v_pk_add_f32 v[78:79], v[78:79], v[114:115]
	ds_bpermute_b32 v115, v160, v79
	ds_bpermute_b32 v114, v160, v78
	s_waitcnt lgkmcnt(0)
	v_pk_add_f32 v[78:79], v[78:79], v[114:115]
	s_nop 0
	v_pk_fma_f32 v[78:79], v[78:79], s[8:9], v[76:77] op_sel_hi:[1,0,1] neg_lo:[1,0,0] neg_hi:[1,0,0]
	s_nop 0
	v_pk_mul_f32 v[76:77], v[78:79], v[78:79]
	s_nop 1
	v_mov_b32_dpp v77, v77 quad_perm:[1,0,3,2] row_mask:0xf bank_mask:0xf bound_ctrl:1
	v_mov_b32_dpp v76, v76 quad_perm:[1,0,3,2] row_mask:0xf bank_mask:0xf bound_ctrl:1
	v_pk_fma_f32 v[76:77], v[78:79], v[78:79], v[76:77]
	s_nop 1
	v_mov_b32_dpp v115, v77 quad_perm:[2,3,0,1] row_mask:0xf bank_mask:0xf bound_ctrl:1
	v_mov_b32_dpp v114, v76 quad_perm:[2,3,0,1] row_mask:0xf bank_mask:0xf bound_ctrl:1
	v_pk_add_f32 v[76:77], v[76:77], v[114:115]
	s_nop 1
	v_mov_b32_dpp v115, v77 row_half_mirror row_mask:0xf bank_mask:0xf bound_ctrl:1
	v_mov_b32_dpp v114, v76 row_half_mirror row_mask:0xf bank_mask:0xf bound_ctrl:1
	v_pk_add_f32 v[76:77], v[76:77], v[114:115]
	s_nop 1
	v_mov_b32_dpp v115, v77 row_mirror row_mask:0xf bank_mask:0xf bound_ctrl:1
	v_mov_b32_dpp v114, v76 row_mirror row_mask:0xf bank_mask:0xf bound_ctrl:1
	v_pk_add_f32 v[76:77], v[76:77], v[114:115]
	ds_bpermute_b32 v115, v159, v77
	ds_bpermute_b32 v114, v159, v76
	s_waitcnt lgkmcnt(0)
	v_pk_add_f32 v[76:77], v[76:77], v[114:115]
	ds_bpermute_b32 v115, v160, v77
	ds_bpermute_b32 v114, v160, v76
	s_waitcnt lgkmcnt(0)
	v_pk_add_f32 v[114:115], v[76:77], v[114:115]
	v_mov_b64_e32 v[76:77], s[26:27]
	v_pk_fma_f32 v[114:115], v[114:115], s[8:9], v[76:77] op_sel_hi:[1,0,0]
	s_nop 0
	v_mul_f32_e32 v116, 0x4b800000, v115
	v_cmp_gt_f32_e64 s[42:43], s1, v115
	v_cmp_gt_f32_e32 vcc, s1, v114
	s_nop 0
	v_cndmask_b32_e64 v115, v115, v116, s[42:43]
	v_rsq_f32_e32 v115, v115
	s_nop 0
	v_mul_f32_e32 v116, 0x45800000, v115
	v_cndmask_b32_e64 v115, v115, v116, s[42:43]
	v_mul_f32_e32 v79, v79, v115
	v_fma_f32 v79, v162, v79, v161
	v_mul_f32_e32 v79, v79, v163
	v_cvt_pk_bf16_f32 v79, v79, s0
	global_store_short v[80:81], v79, off offset:1024
	v_mul_f32_e32 v79, 0x4b800000, v114
	v_cndmask_b32_e32 v79, v114, v79, vcc
	v_rsq_f32_e32 v79, v79
	ds_read_b32 v81, v17 offset:49408
	v_mul_f32_e32 v80, 0x45800000, v79
	v_cndmask_b32_e32 v79, v79, v80, vcc
	v_mul_f32_e32 v78, v78, v79
	v_fma_f32 v80, v162, v78, v161
	v_lshlrev_b64 v[78:79], 10, v[118:119]
	v_lshl_add_u64 v[78:79], v[72:73], 0, v[78:79]
	v_mov_b32_e32 v78, v175
	v_lshlrev_b32_e32 v78, 16, v78
	v_mul_f32_e32 v78, v80, v78
	v_cvt_pk_bf16_f32 v80, v78, s0
	v_lshl_add_u64 v[78:79], v[74:75], 0, v[120:121]
	global_store_short v[78:79], v80, off offset:1024
	v_or_b32_e32 v78, s0, v15
	v_ashrrev_i32_e32 v79, 31, v78
	v_lshlrev_b64 v[114:115], 11, v[78:79]
	v_lshlrev_b64 v[78:79], 10, v[78:79]
	v_lshl_add_u64 v[78:79], v[72:73], 0, v[78:79]
	v_mov_b32_e32 v78, v176
	v_lshl_add_u64 v[116:117], s[6:7], 0, v[114:115]
	v_lshl_add_u64 v[116:117], v[116:117], 0, v[0:1]
	v_mov_b32_e32 v119, v177
	ds_read_b32 v80, v21 offset:49408
	v_lshlrev_b32_e32 v163, 16, v78
	v_lshl_add_u64 v[78:79], v[74:75], 0, v[114:115]
	v_or_b32_e32 v114, s0, v19
	v_ashrrev_i32_e32 v115, 31, v114
	v_lshlrev_b64 v[120:121], 11, v[114:115]
	v_lshl_add_u64 v[164:165], s[6:7], 0, v[120:121]
	v_lshl_add_u64 v[164:165], v[164:165], 0, v[0:1]
	v_mov_b32_e32 v118, v178
	v_add_co_u32_e32 v116, vcc, s4, v116
	s_waitcnt lgkmcnt(0)
	v_pk_add_f32 v[80:81], v[80:81], v[118:119]
	v_addc_co_u32_e32 v117, vcc, 0, v117, vcc
	v_add_co_u32_e32 v118, vcc, s4, v164
	v_mov_b32_e32 v117, v179
	s_nop 0
	v_addc_co_u32_e32 v119, vcc, 0, v165, vcc
	v_mov_b32_e32 v116, v180
	v_pk_add_f32 v[80:81], v[80:81], v[116:117]
	s_nop 1
	v_mov_b32_dpp v117, v81 quad_perm:[1,0,3,2] row_mask:0xf bank_mask:0xf bound_ctrl:1
	v_mov_b32_dpp v116, v80 quad_perm:[1,0,3,2] row_mask:0xf bank_mask:0xf bound_ctrl:1
	v_pk_add_f32 v[116:117], v[80:81], v[116:117]
	s_nop 1
	v_mov_b32_dpp v119, v117 quad_perm:[2,3,0,1] row_mask:0xf bank_mask:0xf bound_ctrl:1
	v_mov_b32_dpp v118, v116 quad_perm:[2,3,0,1] row_mask:0xf bank_mask:0xf bound_ctrl:1
	v_pk_add_f32 v[116:117], v[116:117], v[118:119]
	s_nop 1
	v_mov_b32_dpp v119, v117 row_half_mirror row_mask:0xf bank_mask:0xf bound_ctrl:1
	v_mov_b32_dpp v118, v116 row_half_mirror row_mask:0xf bank_mask:0xf bound_ctrl:1
	v_pk_add_f32 v[116:117], v[116:117], v[118:119]
	s_nop 1
	v_mov_b32_dpp v119, v117 row_mirror row_mask:0xf bank_mask:0xf bound_ctrl:1
	v_mov_b32_dpp v118, v116 row_mirror row_mask:0xf bank_mask:0xf bound_ctrl:1
	v_pk_add_f32 v[116:117], v[116:117], v[118:119]
	ds_bpermute_b32 v119, v159, v117
	ds_bpermute_b32 v118, v159, v116
	s_waitcnt lgkmcnt(0)
	v_pk_add_f32 v[116:117], v[116:117], v[118:119]
	ds_bpermute_b32 v119, v160, v117
	ds_bpermute_b32 v118, v160, v116
	s_waitcnt lgkmcnt(0)
	v_pk_add_f32 v[116:117], v[116:117], v[118:119]
	s_nop 0
	v_pk_fma_f32 v[80:81], v[116:117], s[8:9], v[80:81] op_sel_hi:[1,0,1] neg_lo:[1,0,0] neg_hi:[1,0,0]
	s_nop 0
	v_pk_mul_f32 v[116:117], v[80:81], v[80:81]
	s_nop 1
	v_mov_b32_dpp v117, v117 quad_perm:[1,0,3,2] row_mask:0xf bank_mask:0xf bound_ctrl:1
	v_mov_b32_dpp v116, v116 quad_perm:[1,0,3,2] row_mask:0xf bank_mask:0xf bound_ctrl:1
	v_pk_fma_f32 v[116:117], v[80:81], v[80:81], v[116:117]
	s_nop 1
	v_mov_b32_dpp v119, v117 quad_perm:[2,3,0,1] row_mask:0xf bank_mask:0xf bound_ctrl:1
	v_mov_b32_dpp v118, v116 quad_perm:[2,3,0,1] row_mask:0xf bank_mask:0xf bound_ctrl:1
	v_pk_add_f32 v[116:117], v[116:117], v[118:119]
	s_nop 1
	v_mov_b32_dpp v119, v117 row_half_mirror row_mask:0xf bank_mask:0xf bound_ctrl:1
	v_mov_b32_dpp v118, v116 row_half_mirror row_mask:0xf bank_mask:0xf bound_ctrl:1
	v_pk_add_f32 v[116:117], v[116:117], v[118:119]
	s_nop 1
	v_mov_b32_dpp v119, v117 row_mirror row_mask:0xf bank_mask:0xf bound_ctrl:1
	v_mov_b32_dpp v118, v116 row_mirror row_mask:0xf bank_mask:0xf bound_ctrl:1
	v_pk_add_f32 v[116:117], v[116:117], v[118:119]
	ds_bpermute_b32 v119, v159, v117
	ds_bpermute_b32 v118, v159, v116
	s_waitcnt lgkmcnt(0)
	v_pk_add_f32 v[116:117], v[116:117], v[118:119]
	ds_bpermute_b32 v119, v160, v117
	ds_bpermute_b32 v118, v160, v116
	s_waitcnt lgkmcnt(0)
	v_pk_add_f32 v[116:117], v[116:117], v[118:119]
	s_nop 0
	v_pk_fma_f32 v[116:117], v[116:117], s[8:9], v[76:77] op_sel_hi:[1,0,0]
	s_nop 0
	v_mul_f32_e32 v118, 0x4b800000, v117
	v_cmp_gt_f32_e64 s[42:43], s1, v117
	v_cmp_gt_f32_e32 vcc, s1, v116
	s_nop 0
	v_cndmask_b32_e64 v117, v117, v118, s[42:43]
	v_rsq_f32_e32 v117, v117
	s_nop 0
	v_mul_f32_e32 v118, 0x45800000, v117
	v_cndmask_b32_e64 v117, v117, v118, s[42:43]
	v_mul_f32_e32 v81, v81, v117
	v_fma_f32 v81, v162, v81, v161
	v_mul_f32_e32 v81, v81, v163
	v_cvt_pk_bf16_f32 v81, v81, s0
	global_store_short v[78:79], v81, off offset:1024
	v_mul_f32_e32 v78, 0x4b800000, v116
	v_cndmask_b32_e32 v78, v116, v78, vcc
	v_rsq_f32_e32 v78, v78
	ds_read_b32 v81, v25 offset:49408
	v_mul_f32_e32 v79, 0x45800000, v78
	v_cndmask_b32_e32 v78, v78, v79, vcc
	v_mul_f32_e32 v78, v80, v78
	v_fma_f32 v80, v162, v78, v161
	v_lshlrev_b64 v[78:79], 10, v[114:115]
	v_lshl_add_u64 v[78:79], v[72:73], 0, v[78:79]
	v_mov_b32_e32 v78, v181
	v_lshlrev_b32_e32 v78, 16, v78
	v_mul_f32_e32 v78, v80, v78
	v_cvt_pk_bf16_f32 v80, v78, s0
	v_lshl_add_u64 v[78:79], v[74:75], 0, v[120:121]
	global_store_short v[78:79], v80, off offset:1024
	v_or_b32_e32 v78, s0, v23
	v_ashrrev_i32_e32 v79, 31, v78
	v_lshlrev_b64 v[114:115], 11, v[78:79]
	v_lshlrev_b64 v[78:79], 10, v[78:79]
	v_lshl_add_u64 v[78:79], v[72:73], 0, v[78:79]
	v_mov_b32_e32 v78, v182
	v_lshl_add_u64 v[116:117], s[6:7], 0, v[114:115]
	v_lshl_add_u64 v[116:117], v[116:117], 0, v[0:1]
	v_mov_b32_e32 v119, v183
	ds_read_b32 v80, v29 offset:49408
	v_lshlrev_b32_e32 v163, 16, v78
	v_lshl_add_u64 v[78:79], v[74:75], 0, v[114:115]
	v_or_b32_e32 v114, s0, v27
	v_ashrrev_i32_e32 v115, 31, v114
	v_lshlrev_b64 v[120:121], 11, v[114:115]
	v_lshl_add_u64 v[164:165], s[6:7], 0, v[120:121]
	v_lshl_add_u64 v[164:165], v[164:165], 0, v[0:1]
	v_mov_b32_e32 v118, v184
	v_add_co_u32_e32 v116, vcc, s4, v116
	s_waitcnt lgkmcnt(0)
	v_pk_add_f32 v[80:81], v[80:81], v[118:119]
	v_addc_co_u32_e32 v117, vcc, 0, v117, vcc
	v_add_co_u32_e32 v118, vcc, s4, v164
	v_mov_b32_e32 v117, v185
	s_nop 0
	v_addc_co_u32_e32 v119, vcc, 0, v165, vcc
	v_mov_b32_e32 v116, v186
	v_pk_add_f32 v[80:81], v[80:81], v[116:117]
	s_nop 1
	v_mov_b32_dpp v117, v81 quad_perm:[1,0,3,2] row_mask:0xf bank_mask:0xf bound_ctrl:1
	v_mov_b32_dpp v116, v80 quad_perm:[1,0,3,2] row_mask:0xf bank_mask:0xf bound_ctrl:1
	v_pk_add_f32 v[116:117], v[80:81], v[116:117]
	s_nop 1
	v_mov_b32_dpp v119, v117 quad_perm:[2,3,0,1] row_mask:0xf bank_mask:0xf bound_ctrl:1
	v_mov_b32_dpp v118, v116 quad_perm:[2,3,0,1] row_mask:0xf bank_mask:0xf bound_ctrl:1
	v_pk_add_f32 v[116:117], v[116:117], v[118:119]
	s_nop 1
	v_mov_b32_dpp v119, v117 row_half_mirror row_mask:0xf bank_mask:0xf bound_ctrl:1
	v_mov_b32_dpp v118, v116 row_half_mirror row_mask:0xf bank_mask:0xf bound_ctrl:1
	v_pk_add_f32 v[116:117], v[116:117], v[118:119]
	s_nop 1
	v_mov_b32_dpp v119, v117 row_mirror row_mask:0xf bank_mask:0xf bound_ctrl:1
	v_mov_b32_dpp v118, v116 row_mirror row_mask:0xf bank_mask:0xf bound_ctrl:1
	v_pk_add_f32 v[116:117], v[116:117], v[118:119]
	ds_bpermute_b32 v119, v159, v117
	ds_bpermute_b32 v118, v159, v116
	s_waitcnt lgkmcnt(0)
	v_pk_add_f32 v[116:117], v[116:117], v[118:119]
	ds_bpermute_b32 v119, v160, v117
	ds_bpermute_b32 v118, v160, v116
	s_waitcnt lgkmcnt(0)
	v_pk_add_f32 v[116:117], v[116:117], v[118:119]
	s_nop 0
	v_pk_fma_f32 v[80:81], v[116:117], s[8:9], v[80:81] op_sel_hi:[1,0,1] neg_lo:[1,0,0] neg_hi:[1,0,0]
	s_nop 0
	v_pk_mul_f32 v[116:117], v[80:81], v[80:81]
	s_nop 1
	v_mov_b32_dpp v117, v117 quad_perm:[1,0,3,2] row_mask:0xf bank_mask:0xf bound_ctrl:1
	v_mov_b32_dpp v116, v116 quad_perm:[1,0,3,2] row_mask:0xf bank_mask:0xf bound_ctrl:1
	v_pk_fma_f32 v[116:117], v[80:81], v[80:81], v[116:117]
	s_nop 1
	v_mov_b32_dpp v119, v117 quad_perm:[2,3,0,1] row_mask:0xf bank_mask:0xf bound_ctrl:1
	v_mov_b32_dpp v118, v116 quad_perm:[2,3,0,1] row_mask:0xf bank_mask:0xf bound_ctrl:1
	v_pk_add_f32 v[116:117], v[116:117], v[118:119]
	s_nop 1
	v_mov_b32_dpp v119, v117 row_half_mirror row_mask:0xf bank_mask:0xf bound_ctrl:1
	v_mov_b32_dpp v118, v116 row_half_mirror row_mask:0xf bank_mask:0xf bound_ctrl:1
	v_pk_add_f32 v[116:117], v[116:117], v[118:119]
	s_nop 1
	v_mov_b32_dpp v119, v117 row_mirror row_mask:0xf bank_mask:0xf bound_ctrl:1
	v_mov_b32_dpp v118, v116 row_mirror row_mask:0xf bank_mask:0xf bound_ctrl:1
	v_pk_add_f32 v[116:117], v[116:117], v[118:119]
	ds_bpermute_b32 v119, v159, v117
	ds_bpermute_b32 v118, v159, v116
	s_waitcnt lgkmcnt(0)
	v_pk_add_f32 v[116:117], v[116:117], v[118:119]
	ds_bpermute_b32 v119, v160, v117
	ds_bpermute_b32 v118, v160, v116
	s_waitcnt lgkmcnt(0)
	v_pk_add_f32 v[116:117], v[116:117], v[118:119]
	s_nop 0
	v_pk_fma_f32 v[116:117], v[116:117], s[8:9], v[76:77] op_sel_hi:[1,0,0]
	s_nop 0
	v_mul_f32_e32 v118, 0x4b800000, v117
	v_cmp_gt_f32_e64 s[42:43], s1, v117
	v_cmp_gt_f32_e32 vcc, s1, v116
	s_nop 0
	v_cndmask_b32_e64 v117, v117, v118, s[42:43]
	v_rsq_f32_e32 v117, v117
	s_nop 0
	v_mul_f32_e32 v118, 0x45800000, v117
	v_cndmask_b32_e64 v117, v117, v118, s[42:43]
	v_mul_f32_e32 v81, v81, v117
	v_fma_f32 v81, v162, v81, v161
	v_mul_f32_e32 v81, v81, v163
	v_cvt_pk_bf16_f32 v81, v81, s0
	global_store_short v[78:79], v81, off offset:1024
	v_mul_f32_e32 v78, 0x4b800000, v116
	v_cndmask_b32_e32 v78, v116, v78, vcc
	v_rsq_f32_e32 v78, v78
	ds_read_b32 v117, v33 offset:49408
	ds_read_b32 v116, v123 offset:49408
	v_mul_f32_e32 v79, 0x45800000, v78
	v_cndmask_b32_e32 v78, v78, v79, vcc
	v_mul_f32_e32 v78, v80, v78
	v_fma_f32 v80, v162, v78, v161
	v_lshlrev_b64 v[78:79], 10, v[114:115]
	v_lshl_add_u64 v[78:79], v[72:73], 0, v[78:79]
	v_mov_b32_e32 v78, v187
	v_lshlrev_b32_e32 v78, 16, v78
	v_mul_f32_e32 v78, v80, v78
	v_cvt_pk_bf16_f32 v80, v78, s0
	v_lshl_add_u64 v[78:79], v[74:75], 0, v[120:121]
	global_store_short v[78:79], v80, off offset:1024
	v_or_b32_e32 v78, s0, v31
	v_ashrrev_i32_e32 v79, 31, v78
	v_lshlrev_b64 v[80:81], 11, v[78:79]
	v_lshlrev_b64 v[78:79], 10, v[78:79]
	v_lshl_add_u64 v[78:79], v[72:73], 0, v[78:79]
	v_mov_b32_e32 v78, v188
	v_lshl_add_u64 v[114:115], s[6:7], 0, v[80:81]
	v_lshl_add_u64 v[114:115], v[114:115], 0, v[0:1]
	v_mov_b32_e32 v119, v189
	v_lshl_add_u64 v[80:81], v[74:75], 0, v[80:81]
	v_lshlrev_b32_e32 v163, 16, v78
	v_or_b32_e32 v78, s0, v122
	v_ashrrev_i32_e32 v79, 31, v78
	v_lshlrev_b64 v[120:121], 11, v[78:79]
	v_lshl_add_u64 v[164:165], s[6:7], 0, v[120:121]
	v_lshl_add_u64 v[164:165], v[164:165], 0, v[0:1]
	v_mov_b32_e32 v118, v190
	v_add_co_u32_e32 v114, vcc, s4, v114
	s_waitcnt lgkmcnt(0)
	v_pk_add_f32 v[116:117], v[116:117], v[118:119]
	v_addc_co_u32_e32 v115, vcc, 0, v115, vcc
	v_add_co_u32_e32 v118, vcc, s4, v164
	v_mov_b32_e32 v115, v191
	s_nop 0
	v_addc_co_u32_e32 v119, vcc, 0, v165, vcc
	v_mov_b32_e32 v114, v192
	v_pk_add_f32 v[114:115], v[116:117], v[114:115]
	s_nop 1
	v_mov_b32_dpp v117, v115 quad_perm:[1,0,3,2] row_mask:0xf bank_mask:0xf bound_ctrl:1
	v_mov_b32_dpp v116, v114 quad_perm:[1,0,3,2] row_mask:0xf bank_mask:0xf bound_ctrl:1
	v_pk_add_f32 v[116:117], v[114:115], v[116:117]
	s_nop 1
	v_mov_b32_dpp v119, v117 quad_perm:[2,3,0,1] row_mask:0xf bank_mask:0xf bound_ctrl:1
	v_mov_b32_dpp v118, v116 quad_perm:[2,3,0,1] row_mask:0xf bank_mask:0xf bound_ctrl:1
	v_pk_add_f32 v[116:117], v[116:117], v[118:119]
	s_nop 1
	v_mov_b32_dpp v119, v117 row_half_mirror row_mask:0xf bank_mask:0xf bound_ctrl:1
	v_mov_b32_dpp v118, v116 row_half_mirror row_mask:0xf bank_mask:0xf bound_ctrl:1
	v_pk_add_f32 v[116:117], v[116:117], v[118:119]
	s_nop 1
	v_mov_b32_dpp v119, v117 row_mirror row_mask:0xf bank_mask:0xf bound_ctrl:1
	v_mov_b32_dpp v118, v116 row_mirror row_mask:0xf bank_mask:0xf bound_ctrl:1
	v_pk_add_f32 v[116:117], v[116:117], v[118:119]
	ds_bpermute_b32 v119, v159, v117
	ds_bpermute_b32 v118, v159, v116
	s_waitcnt lgkmcnt(0)
	v_pk_add_f32 v[116:117], v[116:117], v[118:119]
	ds_bpermute_b32 v119, v160, v117
	ds_bpermute_b32 v118, v160, v116
	s_waitcnt lgkmcnt(0)
	v_pk_add_f32 v[116:117], v[116:117], v[118:119]
	s_nop 0
	v_pk_fma_f32 v[114:115], v[116:117], s[8:9], v[114:115] op_sel_hi:[1,0,1] neg_lo:[1,0,0] neg_hi:[1,0,0]
	s_nop 0
	v_pk_mul_f32 v[116:117], v[114:115], v[114:115]
	s_nop 1
	v_mov_b32_dpp v117, v117 quad_perm:[1,0,3,2] row_mask:0xf bank_mask:0xf bound_ctrl:1
	v_mov_b32_dpp v116, v116 quad_perm:[1,0,3,2] row_mask:0xf bank_mask:0xf bound_ctrl:1
	v_pk_fma_f32 v[116:117], v[114:115], v[114:115], v[116:117]
	s_nop 1
	v_mov_b32_dpp v119, v117 quad_perm:[2,3,0,1] row_mask:0xf bank_mask:0xf bound_ctrl:1
	v_mov_b32_dpp v118, v116 quad_perm:[2,3,0,1] row_mask:0xf bank_mask:0xf bound_ctrl:1
	v_pk_add_f32 v[116:117], v[116:117], v[118:119]
	s_nop 1
	v_mov_b32_dpp v119, v117 row_half_mirror row_mask:0xf bank_mask:0xf bound_ctrl:1
	v_mov_b32_dpp v118, v116 row_half_mirror row_mask:0xf bank_mask:0xf bound_ctrl:1
	v_pk_add_f32 v[116:117], v[116:117], v[118:119]
	s_nop 1
	v_mov_b32_dpp v119, v117 row_mirror row_mask:0xf bank_mask:0xf bound_ctrl:1
	v_mov_b32_dpp v118, v116 row_mirror row_mask:0xf bank_mask:0xf bound_ctrl:1
	v_pk_add_f32 v[116:117], v[116:117], v[118:119]
	ds_bpermute_b32 v119, v159, v117
	ds_bpermute_b32 v118, v159, v116
	s_waitcnt lgkmcnt(0)
	v_pk_add_f32 v[116:117], v[116:117], v[118:119]
	ds_bpermute_b32 v119, v160, v117
	ds_bpermute_b32 v118, v160, v116
	s_waitcnt lgkmcnt(0)
	v_pk_add_f32 v[116:117], v[116:117], v[118:119]
	s_nop 0
	v_pk_fma_f32 v[76:77], v[116:117], s[8:9], v[76:77] op_sel_hi:[1,0,0]
	s_nop 0
	v_mul_f32_e32 v116, 0x4b800000, v77
	v_cmp_gt_f32_e64 s[42:43], s1, v77
	v_cmp_gt_f32_e32 vcc, s1, v76
	s_nop 0
	v_cndmask_b32_e64 v77, v77, v116, s[42:43]
	v_rsq_f32_e32 v77, v77
	s_nop 0
	v_mul_f32_e32 v116, 0x45800000, v77
	v_cndmask_b32_e64 v77, v77, v116, s[42:43]
	v_mul_f32_e32 v77, v115, v77
	v_fma_f32 v77, v162, v77, v161
	v_mul_f32_e32 v77, v77, v163
	v_cvt_pk_bf16_f32 v77, v77, s0
	global_store_short v[80:81], v77, off offset:1024
	v_mul_f32_e32 v77, 0x4b800000, v76
	v_cndmask_b32_e32 v76, v76, v77, vcc
	v_rsq_f32_e32 v76, v76
	s_nop 0
	v_mul_f32_e32 v77, 0x45800000, v76
	v_cndmask_b32_e32 v76, v76, v77, vcc
	v_mul_f32_e32 v76, v114, v76
	v_fmac_f32_e32 v161, v162, v76
	v_lshlrev_b64 v[76:77], 10, v[78:79]
	v_lshl_add_u64 v[76:77], v[72:73], 0, v[76:77]
	v_mov_b32_e32 v76, v193
	v_lshlrev_b32_e32 v76, 16, v76
	v_mul_f32_e32 v76, v161, v76
	v_cvt_pk_bf16_f32 v78, v76, s0
	v_lshl_add_u64 v[76:77], v[74:75], 0, v[120:121]
	global_store_short v[76:77], v78, off offset:1024
	s_cbranch_scc1 .LBB0_462

.LBB0_936:
	v_readlane_b32 s0, v255, 21
	v_readlane_b32 s1, v255, 22
	s_and_b64 vcc, exec, s[0:1]
	s_cbranch_vccz .LBB0_973
	s_add_i32 s26, s20, s24
	s_mov_b64 s[20:21], -1
	s_mov_b64 s[28:29], 0
	s_cmp_lt_i32 s26, 1
	s_mov_b64 s[0:1], 0
	s_movk_i32 s50, 0xfff
	s_cbranch_scc1 .LBB0_963
	s_cmp_eq_u32 s26, 1
	s_mov_b64 s[0:1], -1
	s_cbranch_scc0 .LBB0_950
	v_mov_b32_e32 v0, v196
	s_mov_b32 s27, s34
	s_mov_b32 s30, s2
	s_cmpk_gt_i32 s30, 0x2bf
	s_cbranch_scc1 .LBB0_949
	v_ashrrev_i32_e32 v2, 1, v0
	v_readlane_b32 s4, v253, 14
	s_waitcnt vmcnt(11)
	v_and_b32_e32 v233, 0xffffffc0, v2
	v_lshlrev_b32_e32 v2, 1, v0
	s_mul_i32 s0, s54, 0xb00000
	v_readlane_b32 s16, v253, 26
	v_and_b32_e32 v234, 0x80, v2
	v_and_b32_e32 v2, 31, v0
	s_add_u32 s40, s16, s0
	v_or_b32_e32 v3, v234, v2
	v_lshrrev_b32_e32 v6, 4, v0
	v_readlane_b32 s0, v254, 21
	v_or_b32_e32 v4, v233, v2
	v_xor_b32_e32 v6, v6, v0
	s_waitcnt vmcnt(10)
	v_lshlrev_b32_e32 v236, 7, v3
	v_lshlrev_b32_e32 v2, 1, v2
	v_mov_b32_e32 v3, v1
	v_readlane_b32 s1, v254, 22
	v_lshlrev_b32_e32 v6, 3, v6
	v_lshlrev_b32_e32 v5, 3, v0
	v_lshl_add_u64 v[176:177], s[0:1], 0, v[2:3]
	v_bfe_u32 v3, v0, 3, 3
	v_and_b32_e32 v7, 56, v6
	v_lshlrev_b32_e32 v235, 7, v4
	v_and_b32_e32 v2, 4, v3
	v_or_b32_e32 v4, 3, v3
	v_or_b32_e32 v6, 11, v3
	s_waitcnt vmcnt(1)
	v_or_b32_e32 v8, 19, v3
	v_or_b32_e32 v3, 27, v3
	v_and_b32_e32 v5, 56, v5
	v_mul_u32_u24_e32 v10, 0xb00, v3
	v_ashrrev_i32_e32 v3, 3, v0
	v_lshl_or_b32 v12, v3, 10, v5
	v_lshl_or_b32 v237, v3, 6, v7
	v_add_u32_e32 v3, 0x200, v0
	v_ashrrev_i32_e32 v3, 3, v3
	v_bfe_u32 v231, v0, 5, 1
	v_bfe_u32 v232, v0, 1, 3
	v_lshl_or_b32 v14, v3, 10, v5
	v_lshl_or_b32 v238, v3, 6, v7
	v_add_u32_e32 v3, 0x400, v0
	v_add_u32_e32 v0, 0x600, v0
	v_ashrrev_i32_e32 v3, 3, v3
	v_ashrrev_i32_e32 v0, 3, v0
	v_readlane_b32 s17, v253, 27
	v_mul_u32_u24_e32 v2, 0xb00, v2
	v_mul_u32_u24_e32 v4, 0xb00, v4
	v_mul_u32_u24_e32 v6, 0xb00, v6
	v_mul_u32_u24_e32 v8, 0xb00, v8
	s_waitcnt vmcnt(0)
	v_lshl_or_b32 v16, v3, 10, v5
	v_lshl_or_b32 v239, v3, 6, v7
	v_lshl_or_b32 v18, v0, 10, v5
	v_lshl_or_b32 v240, v0, 6, v7
	v_mov_b32_e32 v13, v1
	v_mov_b32_e32 v15, v1
	v_mov_b32_e32 v17, v1
	v_mov_b32_e32 v19, v1
	s_addc_u32 s41, s17, 0
	v_lshl_add_u32 v241, v237, 1, 16
	v_lshl_add_u32 v242, v238, 1, 16
	v_lshl_add_u32 v243, v239, 1, 16
	v_lshl_add_u32 v244, v240, 1, 16
	v_lshlrev_b32_e32 v178, 1, v2
	v_lshlrev_b32_e32 v180, 1, v4
	v_lshlrev_b32_e32 v182, 1, v6
	v_lshlrev_b32_e32 v184, 1, v8
	v_lshlrev_b32_e32 v186, 1, v10
	v_lshlrev_b64 v[188:189], 1, v[12:13]
	v_lshlrev_b64 v[190:191], 1, v[14:15]
	v_lshlrev_b64 v[192:193], 1, v[16:17]
	v_lshlrev_b64 v[194:195], 1, v[18:19]
	v_readlane_b32 s5, v253, 15
	v_readlane_b32 s6, v253, 16
	v_readlane_b32 s7, v253, 17
	v_readlane_b32 s8, v253, 18
	v_readlane_b32 s9, v253, 19
	v_readlane_b32 s10, v253, 20
	v_readlane_b32 s11, v253, 21
	v_readlane_b32 s12, v253, 22
	v_readlane_b32 s13, v253, 23
	v_readlane_b32 s14, v253, 24
	v_readlane_b32 s15, v253, 25
	v_readlane_b32 s18, v253, 28
	v_readlane_b32 s19, v253, 29
	v_lshrrev_b32_e32 v2, 3, v196
	v_lshrrev_b32_e32 v3, 4, v196
	v_xor_b32_e32 v3, v3, v196
	v_and_b32_e32 v3, 7, v3
	v_lshlrev_b32_e32 v3, 4, v3
	v_lshl_or_b32 v168, v2, 11, v3
	v_add_u32_e32 v169, 0x20000, v168
	v_add_u32_e32 v170, 0x40000, v168
	v_add_u32_e32 v171, 0x60000, v168
	v_add_u32_e32 v2, 0, v231
	v_xor_b32_e32 v2, v2, v232
	v_lshlrev_b32_e32 v2, 4, v2
	v_add3_u32 v172, v235, v2, 16
	v_add3_u32 v192, v236, v2, 16
	v_add_u32_e32 v188, 0x10000, v172
	v_add_u32_e32 v237, 0x10000, v192
	v_add_u32_e32 v2, 2, v231
	v_xor_b32_e32 v2, v2, v232
	v_lshlrev_b32_e32 v2, 4, v2
	v_add3_u32 v173, v235, v2, 16
	v_add3_u32 v193, v236, v2, 16
	v_add_u32_e32 v189, 0x10000, v173
	v_add_u32_e32 v238, 0x10000, v193
	v_add_u32_e32 v2, 4, v231
	v_xor_b32_e32 v2, v2, v232
	v_lshlrev_b32_e32 v2, 4, v2
	v_add3_u32 v174, v235, v2, 16
	v_add3_u32 v194, v236, v2, 16
	v_add_u32_e32 v190, 0x10000, v174
	v_add_u32_e32 v239, 0x10000, v194
	v_add_u32_e32 v2, 6, v231
	v_xor_b32_e32 v2, v2, v232
	v_lshlrev_b32_e32 v2, 4, v2
	v_add3_u32 v175, v235, v2, 16
	v_add3_u32 v195, v236, v2, 16
	v_add_u32_e32 v191, 0x10000, v175
	v_add_u32_e32 v240, 0x10000, v195
	s_mov_b32 s44, 0
.LBB0_941:
	s_ashr_i32 s0, s30, 31
	s_lshr_b32 s0, s0, 27
	s_add_i32 s0, s30, s0
	s_and_b32 s1, s0, 0xffffe0
	s_sub_i32 s1, s30, s1
	s_lshl_b32 s0, s0, 3
	s_lshl_b32 s20, s1, 8
	s_and_b32 s0, s0, 0xffffff00
	s_ashr_i32 s21, s20, 31
	s_ashr_i32 s1, s0, 31
	v_readlane_b32 s4, v254, 0
	s_lshl_b64 s[22:23], s[20:21], 11
	s_lshl_b64 s[24:25], s[0:1], 11
	v_readlane_b32 s6, v254, 2
	v_readlane_b32 s7, v254, 3
	s_add_u32 s22, s6, s22
	s_addc_u32 s23, s7, s23
	s_add_u32 s24, s40, s24
	s_addc_u32 s25, s41, s25
	s_waitcnt lgkmcnt(0)
	v_lshrrev_b32_e32 v2, 6, v196
	v_mov_b64_e32 v[16:17], 0
	v_mov_b64_e32 v[18:19], 0
	v_mov_b64_e32 v[20:21], 0
	v_mov_b64_e32 v[22:23], 0
	v_mov_b64_e32 v[24:25], 0
	v_mov_b64_e32 v[26:27], 0
	v_mov_b64_e32 v[28:29], 0
	v_mov_b64_e32 v[30:31], 0
	v_mov_b64_e32 v[32:33], 0
	v_mov_b64_e32 v[34:35], 0
	v_mov_b64_e32 v[36:37], 0
	v_mov_b64_e32 v[38:39], 0
	v_mov_b64_e32 v[40:41], 0
	v_mov_b64_e32 v[42:43], 0
	v_mov_b64_e32 v[44:45], 0
	v_mov_b64_e32 v[46:47], 0
	v_mov_b64_e32 v[48:49], 0
	v_mov_b64_e32 v[50:51], 0
	v_mov_b64_e32 v[52:53], 0
	v_mov_b64_e32 v[54:55], 0
	v_mov_b64_e32 v[56:57], 0
	v_mov_b64_e32 v[58:59], 0
	v_mov_b64_e32 v[60:61], 0
	v_mov_b64_e32 v[62:63], 0
	v_mov_b64_e32 v[64:65], 0
	v_mov_b64_e32 v[66:67], 0
	v_mov_b64_e32 v[68:69], 0
	v_mov_b64_e32 v[70:71], 0
	v_mov_b64_e32 v[72:73], 0
	v_mov_b64_e32 v[74:75], 0
	v_mov_b64_e32 v[76:77], 0
	v_mov_b64_e32 v[78:79], 0
	v_mov_b64_e32 v[80:81], 0
	v_mov_b64_e32 v[82:83], 0
	v_mov_b64_e32 v[84:85], 0
	v_mov_b64_e32 v[86:87], 0
	v_mov_b64_e32 v[88:89], 0
	v_mov_b64_e32 v[90:91], 0
	v_mov_b64_e32 v[92:93], 0
	v_mov_b64_e32 v[94:95], 0
	v_mov_b64_e32 v[96:97], 0
	v_mov_b64_e32 v[98:99], 0
	v_mov_b64_e32 v[100:101], 0
	v_mov_b64_e32 v[102:103], 0
	v_mov_b64_e32 v[104:105], 0
	v_mov_b64_e32 v[106:107], 0
	v_mov_b64_e32 v[108:109], 0
	v_mov_b64_e32 v[110:111], 0
	v_mov_b64_e32 v[112:113], 0
	v_mov_b64_e32 v[114:115], 0
	v_mov_b64_e32 v[116:117], 0
	v_mov_b64_e32 v[118:119], 0
	v_mov_b64_e32 v[120:121], 0
	v_mov_b64_e32 v[122:123], 0
	v_mov_b64_e32 v[124:125], 0
	v_mov_b64_e32 v[126:127], 0
	v_mov_b64_e32 v[128:129], 0
	v_mov_b64_e32 v[130:131], 0
	v_mov_b64_e32 v[132:133], 0
	v_mov_b64_e32 v[134:135], 0
	v_mov_b64_e32 v[136:137], 0
	v_mov_b64_e32 v[138:139], 0
	v_mov_b64_e32 v[140:141], 0
	v_mov_b64_e32 v[142:143], 0
	v_readfirstlane_b32 s42, v2
	s_lshl_b32 s42, s42, 10
	s_add_i32 s42, s42, 16
	s_add_i32 s43, s42, 0x10000
	s_cmp_eq_u32 s44, 1
	s_cbranch_scc1 .Lw13_pfdone
	s_mov_b32 m0, s42
	s_nop 0
	global_load_lds_dwordx4 v168, s[22:23]
	s_add_u32 m0, m0, 0x2000
	s_nop 0
	global_load_lds_dwordx4 v169, s[22:23]
	s_add_u32 m0, m0, 0x2000
	s_nop 0
	global_load_lds_dwordx4 v170, s[22:23]
	s_add_u32 m0, m0, 0x2000
	s_nop 0
	global_load_lds_dwordx4 v171, s[22:23]
	s_add_u32 m0, m0, 0x2000
	s_nop 0
	global_load_lds_dwordx4 v168, s[24:25]
	s_add_u32 m0, m0, 0x2000
	s_nop 0
	global_load_lds_dwordx4 v169, s[24:25]
	s_add_u32 m0, m0, 0x2000
	s_nop 0
	global_load_lds_dwordx4 v170, s[24:25]
	s_add_u32 m0, m0, 0x2000
	s_nop 0
	global_load_lds_dwordx4 v171, s[24:25]
	s_add_u32 s22, s22, 0x80
	s_addc_u32 s23, s23, 0
	s_add_u32 s24, s24, 0x80
	s_addc_u32 s25, s25, 0
	s_branch .Lw13_pfgo
.Lw13_pfdone:
	s_add_u32 s22, s22, 0x80
	s_addc_u32 s23, s23, 0
	s_add_u32 s24, s24, 0x80
	s_addc_u32 s25, s25, 0
.Lw13_pfgo:
	v_mov_b32_e32 v0, v1
	s_mov_b32 s21, 0
	v_readlane_b32 s5, v254, 1
	v_readlane_b32 s8, v254, 4
	v_readlane_b32 s9, v254, 5
	v_readlane_b32 s10, v254, 6
	v_readlane_b32 s11, v254, 7
	v_readlane_b32 s12, v254, 8
	v_readlane_b32 s13, v254, 9
	v_readlane_b32 s14, v254, 10
	v_readlane_b32 s15, v254, 11
	v_readlane_b32 s16, v254, 12
	v_readlane_b32 s17, v254, 13
	v_readlane_b32 s18, v254, 14
	v_readlane_b32 s19, v254, 15
	s_movk_i32 s1, 8

.Lw13_last:
	s_waitcnt vmcnt(0)
	s_barrier
	ds_read_b128 v[4:7], v188
	ds_read_b128 v[8:11], v188 offset:4096
	ds_read_b128 v[12:15], v237 offset:32768
	ds_read_b128 v[246:249], v237 offset:36864
	ds_read_b128 v[214:217], v237 offset:40960
	ds_read_b128 v[218:221], v237 offset:45056
	ds_read_b128 v[144:147], v189
	ds_read_b128 v[148:151], v189 offset:4096
	ds_read_b128 v[152:155], v238 offset:32768
	ds_read_b128 v[156:159], v238 offset:36864
	ds_read_b128 v[160:163], v238 offset:40960
	ds_read_b128 v[164:167], v238 offset:45056
	s_waitcnt lgkmcnt(6)
	s_setprio 1
	v_mfma_f32_32x32x16_bf16 v[112:127], v[4:7], v[12:15], v[112:127]
	v_mfma_f32_32x32x16_bf16 v[80:95], v[8:11], v[12:15], v[80:95]
	v_mfma_f32_32x32x16_bf16 v[128:143], v[4:7], v[246:249], v[128:143]
	v_mfma_f32_32x32x16_bf16 v[96:111], v[8:11], v[246:249], v[96:111]
	v_mfma_f32_32x32x16_bf16 v[64:79], v[4:7], v[214:217], v[64:79]
	v_mfma_f32_32x32x16_bf16 v[16:31], v[8:11], v[214:217], v[16:31]
	v_mfma_f32_32x32x16_bf16 v[48:63], v[4:7], v[218:221], v[48:63]
	v_mfma_f32_32x32x16_bf16 v[32:47], v[8:11], v[218:221], v[32:47]
	s_setprio 0
	ds_read_b128 v[4:7], v190
	ds_read_b128 v[8:11], v190 offset:4096
	ds_read_b128 v[12:15], v239 offset:32768
	ds_read_b128 v[246:249], v239 offset:36864
	ds_read_b128 v[214:217], v239 offset:40960
	ds_read_b128 v[218:221], v239 offset:45056
	s_waitcnt lgkmcnt(6)
	s_setprio 1
	v_mfma_f32_32x32x16_bf16 v[112:127], v[144:147], v[152:155], v[112:127]
	v_mfma_f32_32x32x16_bf16 v[80:95], v[148:151], v[152:155], v[80:95]
	v_mfma_f32_32x32x16_bf16 v[128:143], v[144:147], v[156:159], v[128:143]
	v_mfma_f32_32x32x16_bf16 v[96:111], v[148:151], v[156:159], v[96:111]
	v_mfma_f32_32x32x16_bf16 v[64:79], v[144:147], v[160:163], v[64:79]
	v_mfma_f32_32x32x16_bf16 v[16:31], v[148:151], v[160:163], v[16:31]
	v_mfma_f32_32x32x16_bf16 v[48:63], v[144:147], v[164:167], v[48:63]
	v_mfma_f32_32x32x16_bf16 v[32:47], v[148:151], v[164:167], v[32:47]
	s_setprio 0
	ds_read_b128 v[144:147], v191
	ds_read_b128 v[148:151], v191 offset:4096
	ds_read_b128 v[152:155], v240 offset:32768
	ds_read_b128 v[156:159], v240 offset:36864
	ds_read_b128 v[160:163], v240 offset:40960
	ds_read_b128 v[164:167], v240 offset:45056
	s_waitcnt lgkmcnt(6)
	s_setprio 1
	v_mfma_f32_32x32x16_bf16 v[112:127], v[4:7], v[12:15], v[112:127]
	v_mfma_f32_32x32x16_bf16 v[80:95], v[8:11], v[12:15], v[80:95]
	v_mfma_f32_32x32x16_bf16 v[128:143], v[4:7], v[246:249], v[128:143]
	v_mfma_f32_32x32x16_bf16 v[96:111], v[8:11], v[246:249], v[96:111]
	v_mfma_f32_32x32x16_bf16 v[64:79], v[4:7], v[214:217], v[64:79]
	v_mfma_f32_32x32x16_bf16 v[16:31], v[8:11], v[214:217], v[16:31]
	v_mfma_f32_32x32x16_bf16 v[48:63], v[4:7], v[218:221], v[48:63]
	v_mfma_f32_32x32x16_bf16 v[32:47], v[8:11], v[218:221], v[32:47]
	s_setprio 0
	s_waitcnt lgkmcnt(0)
	s_setprio 1
	v_mfma_f32_32x32x16_bf16 v[112:127], v[144:147], v[152:155], v[112:127]
	v_mfma_f32_32x32x16_bf16 v[80:95], v[148:151], v[152:155], v[80:95]
	v_mfma_f32_32x32x16_bf16 v[128:143], v[144:147], v[156:159], v[128:143]
	v_mfma_f32_32x32x16_bf16 v[96:111], v[148:151], v[156:159], v[96:111]
	v_mfma_f32_32x32x16_bf16 v[64:79], v[144:147], v[160:163], v[64:79]
	v_mfma_f32_32x32x16_bf16 v[16:31], v[148:151], v[160:163], v[16:31]
	v_mfma_f32_32x32x16_bf16 v[48:63], v[144:147], v[164:167], v[48:63]
	v_mfma_f32_32x32x16_bf16 v[32:47], v[148:151], v[164:167], v[32:47]
	s_setprio 0
	s_mov_b32 s44, 0
	s_add_i32 s1, s30, s27
	s_cmpk_gt_i32 s1, 0x2bf
	s_cbranch_scc1 .Lw13_nopf
	s_and_b32 s21, s1, 31
	s_lshl_b32 s21, s21, 19
	s_add_u32 s22, s6, s21
	s_addc_u32 s23, s7, 0
	s_lshr_b32 s21, s1, 5
	s_lshl_b32 s21, s21, 19
	s_add_u32 s24, s40, s21
	s_addc_u32 s25, s41, 0
	s_mov_b32 m0, s42
	s_nop 0
	global_load_lds_dwordx4 v168, s[22:23]
	s_add_u32 m0, m0, 0x2000
	s_nop 0
	global_load_lds_dwordx4 v169, s[22:23]
	s_add_u32 m0, m0, 0x2000
	s_nop 0
	global_load_lds_dwordx4 v170, s[22:23]
	s_add_u32 m0, m0, 0x2000
	s_nop 0
	global_load_lds_dwordx4 v171, s[22:23]
	s_add_u32 m0, m0, 0x2000
	s_nop 0
	global_load_lds_dwordx4 v168, s[24:25]
	s_add_u32 m0, m0, 0x2000
	s_nop 0
	global_load_lds_dwordx4 v169, s[24:25]
	s_add_u32 m0, m0, 0x2000
	s_nop 0
	global_load_lds_dwordx4 v170, s[24:25]
	s_add_u32 m0, m0, 0x2000
	s_nop 0
	global_load_lds_dwordx4 v171, s[24:25]
	s_add_u32 s22, s22, 0x80
	s_addc_u32 s23, s23, 0
	s_add_u32 s24, s24, 0x80
	s_addc_u32 s25, s25, 0
	s_mov_b32 s44, 1
.Lw13_nopf:
	s_nop 7
	v_mul_f32_e32 v2, 0xbfb8aa3b, v112
	v_exp_f32_e32 v4, v2
	v_or_b32_e32 v2, s0, v234
	v_ashrrev_i32_e32 v2, 1, v2
	v_ashrrev_i32_e32 v3, 31, v2
	v_add_f32_e32 v4, 1.0, v4
	v_lshl_add_u64 v[144:145], v[2:3], 1, v[176:177]
	v_add_u32_e32 v0, s20, v233
	s_movk_i32 s7, 0x1600
	v_mul_f32_e32 v3, 0xbfb8aa3b, v113
	v_exp_f32_e32 v3, v3
	v_rcp_f32_e32 v2, v4
	s_nop 0
	v_mul_f32_e32 v2, v112, v2
	v_mad_i64_i32 v[146:147], s[0:1], v0, s7, v[144:145]
	v_mul_f32_e32 v2, v128, v2
	v_add_f32_e32 v5, 1.0, v3
	v_cvt_pk_bf16_f32 v4, v2, s0
	v_mov_b32_e32 v179, v1
	v_lshl_add_u64 v[2:3], v[146:147], 0, v[178:179]
	global_store_short v[2:3], v4, off
	v_rcp_f32_e32 v4, v5
	v_mul_f32_e32 v5, 0xbfb8aa3b, v114
	v_exp_f32_e32 v5, v5
	v_mul_f32_e32 v4, v113, v4
	v_mul_f32_e32 v4, v129, v4
	v_cvt_pk_bf16_f32 v6, v4, s0
	v_add_f32_e32 v7, 1.0, v5
	s_movk_i32 s4, 0x1000
	v_add_co_u32_e32 v4, vcc, s4, v2
	s_movk_i32 s5, 0x2000
	s_nop 0
	v_addc_co_u32_e32 v5, vcc, 0, v3, vcc
	global_store_short v[4:5], v6, off offset:1536
	v_rcp_f32_e32 v6, v7
	v_mul_f32_e32 v7, 0xbfb8aa3b, v115
	v_exp_f32_e32 v7, v7
	v_mul_f32_e32 v6, v114, v6
	v_mul_f32_e32 v6, v130, v6
	v_cvt_pk_bf16_f32 v8, v6, s0
	v_add_f32_e32 v9, 1.0, v7
	v_add_co_u32_e32 v6, vcc, s5, v2
	v_mov_b32_e32 v181, v1
	s_nop 0
	v_addc_co_u32_e32 v7, vcc, 0, v3, vcc
	global_store_short v[6:7], v8, off offset:3072
	v_rcp_f32_e32 v8, v9
	v_mul_f32_e32 v9, 0xbfb8aa3b, v116
	v_exp_f32_e32 v9, v9
	v_mul_f32_e32 v8, v115, v8
	v_mul_f32_e32 v8, v131, v8
	v_cvt_pk_bf16_f32 v10, v8, s0
	v_add_f32_e32 v11, 1.0, v9
	v_lshl_add_u64 v[8:9], v[146:147], 0, v[180:181]
	global_store_short v[8:9], v10, off
	s_mov_b32 s8, 0xb000
	v_rcp_f32_e32 v10, v11
	v_mul_f32_e32 v11, 0xbfb8aa3b, v117
	v_exp_f32_e32 v11, v11
	v_mul_f32_e32 v10, v116, v10
	v_mul_f32_e32 v10, v132, v10
	v_cvt_pk_bf16_f32 v12, v10, s0
	v_add_f32_e32 v13, 1.0, v11
	v_add_co_u32_e32 v10, vcc, s8, v2
	s_mov_b32 s6, 0xd000
	s_nop 0
	v_addc_co_u32_e32 v11, vcc, 0, v3, vcc
	global_store_short v[10:11], v12, off
	v_rcp_f32_e32 v12, v13
	v_mul_f32_e32 v13, 0xbfb8aa3b, v118
	v_exp_f32_e32 v13, v13
	v_mul_f32_e32 v12, v117, v12
	v_mul_f32_e32 v12, v133, v12
	v_cvt_pk_bf16_f32 v14, v12, s0
	v_add_f32_e32 v15, 1.0, v13
	v_add_co_u32_e32 v12, vcc, s36, v2
	v_mov_b32_e32 v183, v1
	s_nop 0
	v_addc_co_u32_e32 v13, vcc, 0, v3, vcc
	global_store_short v[12:13], v14, off offset:1536
	v_rcp_f32_e32 v14, v15
	v_mul_f32_e32 v15, 0xbfb8aa3b, v119
	v_exp_f32_e32 v15, v15
	v_mul_f32_e32 v14, v118, v14
	v_mul_f32_e32 v14, v134, v14
	v_cvt_pk_bf16_f32 v112, v14, s0
	v_add_f32_e32 v113, 1.0, v15
	v_add_co_u32_e32 v14, vcc, s6, v2
	s_mov_b32 s9, 0x16000
	s_nop 0
	v_addc_co_u32_e32 v15, vcc, 0, v3, vcc
	global_store_short v[14:15], v112, off offset:3072
	v_rcp_f32_e32 v112, v113
	v_mul_f32_e32 v113, 0xbfb8aa3b, v120
	v_exp_f32_e32 v113, v113
	v_mul_f32_e32 v112, v119, v112
	v_mul_f32_e32 v112, v135, v112
	v_cvt_pk_bf16_f32 v114, v112, s0
	v_add_f32_e32 v115, 1.0, v113
	v_lshl_add_u64 v[112:113], v[146:147], 0, v[182:183]
	global_store_short v[112:113], v114, off
	s_mov_b32 s10, 0x17000
	v_rcp_f32_e32 v114, v115
	v_mul_f32_e32 v115, 0xbfb8aa3b, v121
	v_exp_f32_e32 v115, v115
	v_mul_f32_e32 v114, v120, v114
	v_mul_f32_e32 v114, v136, v114
	v_cvt_pk_bf16_f32 v116, v114, s0
	v_add_f32_e32 v117, 1.0, v115
	v_add_co_u32_e32 v114, vcc, s9, v2
	v_mov_b32_e32 v185, v1
	s_nop 0
	v_addc_co_u32_e32 v115, vcc, 0, v3, vcc
	global_store_short v[114:115], v116, off
	v_rcp_f32_e32 v116, v117
	v_mul_f32_e32 v117, 0xbfb8aa3b, v122
	v_exp_f32_e32 v117, v117
	v_mul_f32_e32 v116, v121, v116
	v_mul_f32_e32 v116, v137, v116
	v_cvt_pk_bf16_f32 v118, v116, s0
	v_add_f32_e32 v119, 1.0, v117
	v_add_co_u32_e32 v116, vcc, s10, v2
	s_mov_b32 s11, 0x21000
	s_nop 0
	v_addc_co_u32_e32 v117, vcc, 0, v3, vcc
	global_store_short v[116:117], v118, off offset:1536
	v_rcp_f32_e32 v118, v119
	v_mul_f32_e32 v119, 0xbfb8aa3b, v123
	v_exp_f32_e32 v119, v119
	v_mul_f32_e32 v118, v122, v118
	v_mul_f32_e32 v118, v138, v118
	v_cvt_pk_bf16_f32 v120, v118, s0
	v_add_f32_e32 v121, 1.0, v119
	v_add_co_u32_e32 v118, vcc, s35, v2
	s_mov_b32 s12, 0x22000
	s_nop 0
	v_addc_co_u32_e32 v119, vcc, 0, v3, vcc
	global_store_short v[118:119], v120, off offset:3072
	v_rcp_f32_e32 v120, v121
	v_mul_f32_e32 v121, 0xbfb8aa3b, v124
	v_exp_f32_e32 v121, v121
	v_mul_f32_e32 v120, v123, v120
	v_mul_f32_e32 v120, v139, v120
	v_cvt_pk_bf16_f32 v122, v120, s0
	v_add_f32_e32 v123, 1.0, v121
	v_lshl_add_u64 v[120:121], v[146:147], 0, v[184:185]
	global_store_short v[120:121], v122, off
	s_mov_b32 s13, 0x23000
	v_rcp_f32_e32 v122, v123
	v_mul_f32_e32 v123, 0xbfb8aa3b, v125
	v_exp_f32_e32 v123, v123
	v_mul_f32_e32 v122, v124, v122
	v_mul_f32_e32 v122, v140, v122
	v_cvt_pk_bf16_f32 v124, v122, s0
	v_add_f32_e32 v128, 1.0, v123
	v_add_co_u32_e32 v122, vcc, s11, v2
	v_mov_b32_e32 v187, v1
	s_nop 0
	v_addc_co_u32_e32 v123, vcc, 0, v3, vcc
	global_store_short v[122:123], v124, off
	v_rcp_f32_e32 v124, v128
	v_mul_f32_e32 v128, 0xbfb8aa3b, v126
	v_exp_f32_e32 v128, v128
	v_mul_f32_e32 v124, v125, v124
	v_mul_f32_e32 v124, v141, v124
	v_cvt_pk_bf16_f32 v129, v124, s0
	v_add_f32_e32 v128, 1.0, v128
	v_add_co_u32_e32 v124, vcc, s12, v2
	v_or_b32_e32 v0, 32, v0
	s_nop 0
	v_addc_co_u32_e32 v125, vcc, 0, v3, vcc
	global_store_short v[124:125], v129, off offset:1536
	v_rcp_f32_e32 v128, v128
	v_mul_f32_e32 v129, 0xbfb8aa3b, v127
	v_exp_f32_e32 v129, v129
	v_mul_f32_e32 v126, v126, v128
	v_mul_f32_e32 v126, v142, v126
	v_cvt_pk_bf16_f32 v126, v126, s0
	v_add_f32_e32 v130, 1.0, v129
	v_add_co_u32_e32 v128, vcc, s13, v2
	s_add_i32 s30, s30, s27
	s_nop 0
	v_addc_co_u32_e32 v129, vcc, 0, v3, vcc
	global_store_short v[128:129], v126, off offset:3072
	v_rcp_f32_e32 v126, v130
	s_nop 0
	v_mul_f32_e32 v126, v127, v126
	v_mul_f32_e32 v126, v143, v126
	v_cvt_pk_bf16_f32 v130, v126, s0
	v_mul_f32_e32 v126, 0xbfb8aa3b, v80
	v_exp_f32_e32 v131, v126
	v_lshl_add_u64 v[126:127], v[146:147], 0, v[186:187]
	global_store_short v[126:127], v130, off
	v_mad_i64_i32 v[132:133], s[0:1], v0, s7, v[144:145]
	v_add_f32_e32 v130, 1.0, v131
	s_cmpk_gt_i32 s30, 0x2bf
	v_mul_f32_e32 v131, 0xbfb8aa3b, v81
	v_exp_f32_e32 v131, v131
	v_rcp_f32_e32 v0, v130
	s_nop 0
	v_mul_f32_e32 v0, v80, v0
	v_add_f32_e32 v80, 1.0, v131
	v_mul_f32_e32 v0, v96, v0
	s_nop 0
	v_cvt_pk_bf16_f32 v0, v0, s0
	v_lshl_add_u64 v[130:131], v[132:133], 0, v[178:179]
	global_store_short v[130:131], v0, off
	v_rcp_f32_e32 v0, v80
	v_mul_f32_e32 v80, 0xbfb8aa3b, v82
	v_exp_f32_e32 v80, v80
	v_mul_f32_e32 v0, v81, v0
	v_mul_f32_e32 v0, v97, v0
	v_cvt_pk_bf16_f32 v0, v0, s0
	v_add_f32_e32 v96, 1.0, v80
	v_add_co_u32_e32 v80, vcc, s4, v130
	s_nop 1
	v_addc_co_u32_e32 v81, vcc, 0, v131, vcc
	global_store_short v[80:81], v0, off offset:1536
	v_rcp_f32_e32 v0, v96
	v_mul_f32_e32 v96, 0xbfb8aa3b, v83
	v_exp_f32_e32 v96, v96
	v_mul_f32_e32 v0, v82, v0
	v_mul_f32_e32 v0, v98, v0
	v_cvt_pk_bf16_f32 v0, v0, s0
	v_add_f32_e32 v82, 1.0, v96
	v_add_co_u32_e32 v96, vcc, s5, v130
	s_nop 1
	v_addc_co_u32_e32 v97, vcc, 0, v131, vcc
	global_store_short v[96:97], v0, off offset:3072
	v_mul_f32_e32 v98, 0xbfb8aa3b, v84
	v_exp_f32_e32 v98, v98
	v_rcp_f32_e32 v0, v82
	s_nop 0
	v_mul_f32_e32 v0, v83, v0
	v_add_f32_e32 v98, 1.0, v98
	v_mul_f32_e32 v0, v99, v0
	s_nop 0
	v_cvt_pk_bf16_f32 v0, v0, s0
	v_lshl_add_u64 v[82:83], v[132:133], 0, v[180:181]
	global_store_short v[82:83], v0, off
	v_rcp_f32_e32 v0, v98
	v_mul_f32_e32 v98, 0xbfb8aa3b, v85
	v_exp_f32_e32 v98, v98
	v_mul_f32_e32 v0, v84, v0
	v_mul_f32_e32 v0, v100, v0
	v_cvt_pk_bf16_f32 v0, v0, s0
	v_add_f32_e32 v84, 1.0, v98
	v_add_co_u32_e32 v98, vcc, s8, v130
	s_nop 1
	v_addc_co_u32_e32 v99, vcc, 0, v131, vcc
	global_store_short v[98:99], v0, off
	v_rcp_f32_e32 v0, v84
	v_mul_f32_e32 v84, 0xbfb8aa3b, v86
	v_exp_f32_e32 v84, v84
	v_mul_f32_e32 v0, v85, v0
	v_mul_f32_e32 v0, v101, v0
	v_cvt_pk_bf16_f32 v0, v0, s0
	v_add_f32_e32 v100, 1.0, v84
	v_add_co_u32_e32 v84, vcc, s36, v130
	s_nop 1
	v_addc_co_u32_e32 v85, vcc, 0, v131, vcc
	global_store_short v[84:85], v0, off offset:1536
	v_rcp_f32_e32 v0, v100
	v_mul_f32_e32 v100, 0xbfb8aa3b, v87
	v_exp_f32_e32 v100, v100
	v_mul_f32_e32 v0, v86, v0
	v_mul_f32_e32 v0, v102, v0
	v_cvt_pk_bf16_f32 v0, v0, s0
	v_add_f32_e32 v86, 1.0, v100
	v_add_co_u32_e32 v100, vcc, s6, v130
	s_nop 1
	v_addc_co_u32_e32 v101, vcc, 0, v131, vcc
	global_store_short v[100:101], v0, off offset:3072
	v_mul_f32_e32 v102, 0xbfb8aa3b, v88
	v_exp_f32_e32 v102, v102
	v_rcp_f32_e32 v0, v86
	s_nop 0
	v_mul_f32_e32 v0, v87, v0
	v_add_f32_e32 v102, 1.0, v102
	v_mul_f32_e32 v0, v103, v0
	s_nop 0
	v_cvt_pk_bf16_f32 v0, v0, s0
	v_lshl_add_u64 v[86:87], v[132:133], 0, v[182:183]
	global_store_short v[86:87], v0, off
	v_rcp_f32_e32 v0, v102
	v_mul_f32_e32 v102, 0xbfb8aa3b, v89
	v_exp_f32_e32 v102, v102
	v_mul_f32_e32 v0, v88, v0
	v_mul_f32_e32 v0, v104, v0
	v_cvt_pk_bf16_f32 v0, v0, s0
	v_add_f32_e32 v88, 1.0, v102
	v_add_co_u32_e32 v102, vcc, s9, v130
	s_nop 1
	v_addc_co_u32_e32 v103, vcc, 0, v131, vcc
	global_store_short v[102:103], v0, off
	v_rcp_f32_e32 v0, v88
	v_mul_f32_e32 v88, 0xbfb8aa3b, v90
	v_exp_f32_e32 v88, v88
	v_mul_f32_e32 v0, v89, v0
	v_mul_f32_e32 v0, v105, v0
	v_cvt_pk_bf16_f32 v0, v0, s0
	v_add_f32_e32 v104, 1.0, v88
	v_add_co_u32_e32 v88, vcc, s10, v130
	s_nop 1
	v_addc_co_u32_e32 v89, vcc, 0, v131, vcc
	global_store_short v[88:89], v0, off offset:1536
	v_rcp_f32_e32 v0, v104
	v_mul_f32_e32 v104, 0xbfb8aa3b, v91
	v_exp_f32_e32 v104, v104
	v_mul_f32_e32 v0, v90, v0
	v_mul_f32_e32 v0, v106, v0
	v_cvt_pk_bf16_f32 v0, v0, s0
	v_add_f32_e32 v90, 1.0, v104
	v_add_co_u32_e32 v104, vcc, s35, v130
	s_nop 1
	v_addc_co_u32_e32 v105, vcc, 0, v131, vcc
	global_store_short v[104:105], v0, off offset:3072
	v_mul_f32_e32 v106, 0xbfb8aa3b, v92
	v_exp_f32_e32 v106, v106
	v_rcp_f32_e32 v0, v90
	s_nop 0
	v_mul_f32_e32 v0, v91, v0
	v_add_f32_e32 v106, 1.0, v106
	v_mul_f32_e32 v0, v107, v0
	s_nop 0
	v_cvt_pk_bf16_f32 v0, v0, s0
	v_lshl_add_u64 v[90:91], v[132:133], 0, v[184:185]
	global_store_short v[90:91], v0, off
	v_rcp_f32_e32 v0, v106
	v_mul_f32_e32 v106, 0xbfb8aa3b, v93
	v_exp_f32_e32 v106, v106
	v_mul_f32_e32 v0, v92, v0
	v_mul_f32_e32 v0, v108, v0
	v_cvt_pk_bf16_f32 v0, v0, s0
	v_add_f32_e32 v92, 1.0, v106
	v_add_co_u32_e32 v106, vcc, s11, v130
	s_nop 1
	v_addc_co_u32_e32 v107, vcc, 0, v131, vcc
	global_store_short v[106:107], v0, off
	v_rcp_f32_e32 v0, v92
	v_mul_f32_e32 v92, 0xbfb8aa3b, v94
	v_exp_f32_e32 v92, v92
	v_mul_f32_e32 v0, v93, v0
	v_mul_f32_e32 v0, v109, v0
	v_cvt_pk_bf16_f32 v0, v0, s0
	v_add_f32_e32 v108, 1.0, v92
	v_add_co_u32_e32 v92, vcc, s12, v130
	s_nop 1
	v_addc_co_u32_e32 v93, vcc, 0, v131, vcc
	global_store_short v[92:93], v0, off offset:1536
	v_rcp_f32_e32 v0, v108
	v_mul_f32_e32 v108, 0xbfb8aa3b, v95
	v_exp_f32_e32 v108, v108
	v_mul_f32_e32 v0, v94, v0
	v_mul_f32_e32 v0, v110, v0
	v_cvt_pk_bf16_f32 v0, v0, s0
	v_add_f32_e32 v94, 1.0, v108
	v_add_co_u32_e32 v108, vcc, s13, v130
	s_nop 1
	v_addc_co_u32_e32 v109, vcc, 0, v131, vcc
	global_store_short v[108:109], v0, off offset:3072
	v_mul_f32_e32 v110, 0xbfb8aa3b, v64
	v_exp_f32_e32 v110, v110
	v_rcp_f32_e32 v0, v94
	s_nop 0
	v_mul_f32_e32 v0, v95, v0
	v_add_f32_e32 v110, 1.0, v110
	v_mul_f32_e32 v0, v111, v0
	s_nop 0
	v_cvt_pk_bf16_f32 v0, v0, s0
	v_lshl_add_u64 v[94:95], v[132:133], 0, v[186:187]
	global_store_short v[94:95], v0, off
	v_mul_f32_e32 v111, 0xbfb8aa3b, v65
	v_exp_f32_e32 v111, v111
	v_rcp_f32_e32 v0, v110
	s_nop 0
	v_mul_f32_e32 v0, v64, v0
	v_add_f32_e32 v64, 1.0, v111
	v_mul_f32_e32 v0, v48, v0
	v_cvt_pk_bf16_f32 v0, v0, s0
	global_store_short v[2:3], v0, off offset:64
	v_mul_f32_e32 v3, 0xbfb8aa3b, v66
	v_exp_f32_e32 v3, v3
	v_rcp_f32_e32 v0, v64
	v_add_f32_e32 v2, 1.0, v3
	v_mul_f32_e32 v0, v65, v0
	v_mul_f32_e32 v0, v49, v0
	v_cvt_pk_bf16_f32 v0, v0, s0
	global_store_short v[4:5], v0, off offset:1600
	v_mul_f32_e32 v3, 0xbfb8aa3b, v67
	v_exp_f32_e32 v3, v3
	v_rcp_f32_e32 v0, v2
	s_nop 0
	v_mul_f32_e32 v0, v66, v0
	v_add_f32_e32 v2, 1.0, v3
	v_mul_f32_e32 v0, v50, v0
	v_cvt_pk_bf16_f32 v0, v0, s0
	global_store_short v[6:7], v0, off offset:3136
	v_mul_f32_e32 v3, 0xbfb8aa3b, v68
	v_exp_f32_e32 v3, v3
	v_rcp_f32_e32 v0, v2
	s_nop 0
	v_mul_f32_e32 v0, v67, v0
	v_add_f32_e32 v2, 1.0, v3
	v_mul_f32_e32 v0, v51, v0
	v_cvt_pk_bf16_f32 v0, v0, s0
	global_store_short v[8:9], v0, off offset:64
	v_mul_f32_e32 v3, 0xbfb8aa3b, v69
	v_exp_f32_e32 v3, v3
	v_rcp_f32_e32 v0, v2
	s_nop 0
	v_mul_f32_e32 v0, v68, v0
	v_add_f32_e32 v2, 1.0, v3
	v_mul_f32_e32 v0, v52, v0
	v_cvt_pk_bf16_f32 v0, v0, s0
	global_store_short v[10:11], v0, off offset:64
	v_mul_f32_e32 v3, 0xbfb8aa3b, v70
	v_exp_f32_e32 v3, v3
	v_rcp_f32_e32 v0, v2
	s_nop 0
	v_mul_f32_e32 v0, v69, v0
	v_add_f32_e32 v2, 1.0, v3
	v_mul_f32_e32 v0, v53, v0
	v_cvt_pk_bf16_f32 v0, v0, s0
	global_store_short v[12:13], v0, off offset:1600
	v_mul_f32_e32 v3, 0xbfb8aa3b, v71
	v_exp_f32_e32 v3, v3
	v_rcp_f32_e32 v0, v2
	s_nop 0
	v_mul_f32_e32 v0, v70, v0
	v_add_f32_e32 v2, 1.0, v3
	v_mul_f32_e32 v0, v54, v0
	v_cvt_pk_bf16_f32 v0, v0, s0
	global_store_short v[14:15], v0, off offset:3136
	v_mul_f32_e32 v3, 0xbfb8aa3b, v72
	v_exp_f32_e32 v3, v3
	v_rcp_f32_e32 v0, v2
	s_nop 0
	v_mul_f32_e32 v0, v71, v0
	v_add_f32_e32 v2, 1.0, v3
	v_mul_f32_e32 v0, v55, v0
	v_cvt_pk_bf16_f32 v0, v0, s0
	global_store_short v[112:113], v0, off offset:64
	v_mul_f32_e32 v3, 0xbfb8aa3b, v73
	v_exp_f32_e32 v3, v3
	v_rcp_f32_e32 v0, v2
	s_nop 0
	v_mul_f32_e32 v0, v72, v0
	v_add_f32_e32 v2, 1.0, v3
	v_mul_f32_e32 v0, v56, v0
	v_cvt_pk_bf16_f32 v0, v0, s0
	global_store_short v[114:115], v0, off offset:64
	v_mul_f32_e32 v3, 0xbfb8aa3b, v74
	v_exp_f32_e32 v3, v3
	v_rcp_f32_e32 v0, v2
	s_nop 0
	v_mul_f32_e32 v0, v73, v0
	v_add_f32_e32 v2, 1.0, v3
	v_mul_f32_e32 v0, v57, v0
	v_cvt_pk_bf16_f32 v0, v0, s0
	global_store_short v[116:117], v0, off offset:1600
	v_mul_f32_e32 v3, 0xbfb8aa3b, v75
	v_exp_f32_e32 v3, v3
	v_rcp_f32_e32 v0, v2
	s_nop 0
	v_mul_f32_e32 v0, v74, v0
	v_add_f32_e32 v2, 1.0, v3
	v_mul_f32_e32 v0, v58, v0
	v_cvt_pk_bf16_f32 v0, v0, s0
	global_store_short v[118:119], v0, off offset:3136
	v_mul_f32_e32 v3, 0xbfb8aa3b, v76
	v_exp_f32_e32 v3, v3
	v_rcp_f32_e32 v0, v2
	s_nop 0
	v_mul_f32_e32 v0, v75, v0
	v_add_f32_e32 v2, 1.0, v3
	v_mul_f32_e32 v0, v59, v0
	v_cvt_pk_bf16_f32 v0, v0, s0
	global_store_short v[120:121], v0, off offset:64
	v_mul_f32_e32 v3, 0xbfb8aa3b, v77
	v_exp_f32_e32 v3, v3
	v_rcp_f32_e32 v0, v2
	s_nop 0
	v_mul_f32_e32 v0, v76, v0
	v_add_f32_e32 v2, 1.0, v3
	v_mul_f32_e32 v0, v60, v0
	v_cvt_pk_bf16_f32 v0, v0, s0
	global_store_short v[122:123], v0, off offset:64
	v_mul_f32_e32 v3, 0xbfb8aa3b, v78
	v_exp_f32_e32 v3, v3
	v_rcp_f32_e32 v0, v2
	s_nop 0
	v_mul_f32_e32 v0, v77, v0
	v_add_f32_e32 v2, 1.0, v3
	v_mul_f32_e32 v0, v61, v0
	v_cvt_pk_bf16_f32 v0, v0, s0
	global_store_short v[124:125], v0, off offset:1600
	v_mul_f32_e32 v3, 0xbfb8aa3b, v79
	v_exp_f32_e32 v3, v3
	v_rcp_f32_e32 v0, v2
	s_nop 0
	v_mul_f32_e32 v0, v78, v0
	v_add_f32_e32 v2, 1.0, v3
	v_mul_f32_e32 v0, v62, v0
	v_cvt_pk_bf16_f32 v0, v0, s0
	global_store_short v[128:129], v0, off offset:3136
	v_mul_f32_e32 v3, 0xbfb8aa3b, v16
	v_exp_f32_e32 v3, v3
	v_rcp_f32_e32 v0, v2
	s_nop 0
	v_mul_f32_e32 v0, v79, v0
	v_add_f32_e32 v2, 1.0, v3
	v_mul_f32_e32 v0, v63, v0
	v_cvt_pk_bf16_f32 v0, v0, s0
	global_store_short v[126:127], v0, off offset:64
	v_mul_f32_e32 v3, 0xbfb8aa3b, v17
	v_exp_f32_e32 v3, v3
	v_rcp_f32_e32 v0, v2
	s_nop 0
	v_mul_f32_e32 v0, v16, v0
	v_add_f32_e32 v2, 1.0, v3
	v_mul_f32_e32 v0, v32, v0
	v_cvt_pk_bf16_f32 v0, v0, s0
	global_store_short v[130:131], v0, off offset:64
	v_mul_f32_e32 v3, 0xbfb8aa3b, v18
	v_exp_f32_e32 v3, v3
	v_rcp_f32_e32 v0, v2
	s_nop 0
	v_mul_f32_e32 v0, v17, v0
	v_add_f32_e32 v2, 1.0, v3
	v_mul_f32_e32 v0, v33, v0
	v_cvt_pk_bf16_f32 v0, v0, s0
	global_store_short v[80:81], v0, off offset:1600
	v_mul_f32_e32 v3, 0xbfb8aa3b, v19
	v_exp_f32_e32 v3, v3
	v_rcp_f32_e32 v0, v2
	s_nop 0
	v_mul_f32_e32 v0, v18, v0
	v_add_f32_e32 v2, 1.0, v3
	v_mul_f32_e32 v0, v34, v0
	v_cvt_pk_bf16_f32 v0, v0, s0
	global_store_short v[96:97], v0, off offset:3136
	v_mul_f32_e32 v3, 0xbfb8aa3b, v20
	v_exp_f32_e32 v3, v3
	v_rcp_f32_e32 v0, v2
	s_nop 0
	v_mul_f32_e32 v0, v19, v0
	v_add_f32_e32 v2, 1.0, v3
	v_mul_f32_e32 v0, v35, v0
	v_cvt_pk_bf16_f32 v0, v0, s0
	global_store_short v[82:83], v0, off offset:64
	v_mul_f32_e32 v3, 0xbfb8aa3b, v21
	v_exp_f32_e32 v3, v3
	v_rcp_f32_e32 v0, v2
	s_nop 0
	v_mul_f32_e32 v0, v20, v0
	v_add_f32_e32 v2, 1.0, v3
	v_mul_f32_e32 v0, v36, v0
	v_cvt_pk_bf16_f32 v0, v0, s0
	global_store_short v[98:99], v0, off offset:64
	v_mul_f32_e32 v3, 0xbfb8aa3b, v22
	v_exp_f32_e32 v3, v3
	v_rcp_f32_e32 v0, v2
	s_nop 0
	v_mul_f32_e32 v0, v21, v0
	v_add_f32_e32 v2, 1.0, v3
	v_mul_f32_e32 v0, v37, v0
	v_cvt_pk_bf16_f32 v0, v0, s0
	global_store_short v[84:85], v0, off offset:1600
	v_mul_f32_e32 v3, 0xbfb8aa3b, v23
	v_exp_f32_e32 v3, v3
	v_rcp_f32_e32 v0, v2
	s_nop 0
	v_mul_f32_e32 v0, v22, v0
	v_add_f32_e32 v2, 1.0, v3
	v_mul_f32_e32 v0, v38, v0
	v_cvt_pk_bf16_f32 v0, v0, s0
	global_store_short v[100:101], v0, off offset:3136
	v_mul_f32_e32 v3, 0xbfb8aa3b, v24
	v_exp_f32_e32 v3, v3
	v_rcp_f32_e32 v0, v2
	s_nop 0
	v_mul_f32_e32 v0, v23, v0
	v_add_f32_e32 v2, 1.0, v3
	v_mul_f32_e32 v0, v39, v0
	v_cvt_pk_bf16_f32 v0, v0, s0
	global_store_short v[86:87], v0, off offset:64
	v_mul_f32_e32 v3, 0xbfb8aa3b, v25
	v_exp_f32_e32 v3, v3
	v_rcp_f32_e32 v0, v2
	s_nop 0
	v_mul_f32_e32 v0, v24, v0
	v_add_f32_e32 v2, 1.0, v3
	v_mul_f32_e32 v0, v40, v0
	v_cvt_pk_bf16_f32 v0, v0, s0
	global_store_short v[102:103], v0, off offset:64
	v_mul_f32_e32 v3, 0xbfb8aa3b, v26
	v_exp_f32_e32 v3, v3
	v_rcp_f32_e32 v0, v2
	s_nop 0
	v_mul_f32_e32 v0, v25, v0
	v_add_f32_e32 v2, 1.0, v3
	v_mul_f32_e32 v0, v41, v0
	v_cvt_pk_bf16_f32 v0, v0, s0
	global_store_short v[88:89], v0, off offset:1600
	v_mul_f32_e32 v3, 0xbfb8aa3b, v27
	v_exp_f32_e32 v3, v3
	v_rcp_f32_e32 v0, v2
	s_nop 0
	v_mul_f32_e32 v0, v26, v0
	v_add_f32_e32 v2, 1.0, v3
	v_mul_f32_e32 v0, v42, v0
	v_cvt_pk_bf16_f32 v0, v0, s0
	global_store_short v[104:105], v0, off offset:3136
	v_mul_f32_e32 v3, 0xbfb8aa3b, v28
	v_exp_f32_e32 v3, v3
	v_rcp_f32_e32 v0, v2
	s_nop 0
	v_mul_f32_e32 v0, v27, v0
	v_add_f32_e32 v2, 1.0, v3
	v_mul_f32_e32 v0, v43, v0
	v_cvt_pk_bf16_f32 v0, v0, s0
	global_store_short v[90:91], v0, off offset:64
	v_mul_f32_e32 v3, 0xbfb8aa3b, v29
	v_exp_f32_e32 v3, v3
	v_rcp_f32_e32 v0, v2
	s_nop 0
	v_mul_f32_e32 v0, v28, v0
	v_add_f32_e32 v2, 1.0, v3
	v_mul_f32_e32 v0, v44, v0
	v_cvt_pk_bf16_f32 v0, v0, s0
	global_store_short v[106:107], v0, off offset:64
	v_mul_f32_e32 v3, 0xbfb8aa3b, v30
	v_exp_f32_e32 v3, v3
	v_rcp_f32_e32 v0, v2
	s_nop 0
	v_mul_f32_e32 v0, v29, v0
	v_add_f32_e32 v2, 1.0, v3
	v_mul_f32_e32 v0, v45, v0
	v_cvt_pk_bf16_f32 v0, v0, s0
	global_store_short v[92:93], v0, off offset:1600
	v_mul_f32_e32 v3, 0xbfb8aa3b, v31
	v_exp_f32_e32 v3, v3
	v_rcp_f32_e32 v0, v2
	s_nop 0
	v_mul_f32_e32 v0, v30, v0
	v_add_f32_e32 v2, 1.0, v3
	v_mul_f32_e32 v0, v46, v0
	v_cvt_pk_bf16_f32 v0, v0, s0
	global_store_short v[108:109], v0, off offset:3136
	v_rcp_f32_e32 v0, v2
	s_nop 0
	v_mul_f32_e32 v0, v31, v0
	v_mul_f32_e32 v0, v47, v0
	v_cvt_pk_bf16_f32 v0, v0, s0
	global_store_short v[94:95], v0, off offset:64
	s_cbranch_scc0 .LBB0_941

.LBB0_1022:
	v_lshl_add_u64 v[26:27], v[24:25], 0, s[28:29]
	global_load_dwordx4 v[28:31], v[26:27], off nt
	v_mov_b32_e32 v244, 0x6000
	v_mov_b32_e32 v245, 0
	v_lshl_add_u64 v[246:247], v[26:27], 0, v[244:245]
	global_load_dwordx4 v[218:221], v[246:247], off
	v_lshl_add_u64 v[246:247], v[246:247], 0, v[244:245]
	global_load_dwordx4 v[236:239], v[246:247], off
	v_lshl_add_u64 v[246:247], v[246:247], 0, v[244:245]
	global_load_dwordx4 v[240:243], v[246:247], off
	v_lshl_add_u64 v[246:247], v[246:247], 0, v[244:245]
	global_load_dwordx4 v[214:217], v[246:247], off
	v_lshl_add_u64 v[246:247], v[246:247], 0, v[244:245]
	global_load_dwordx4 v[218:221], v[246:247], off
	v_lshl_add_u64 v[246:247], v[246:247], 0, v[244:245]
	global_load_dwordx4 v[236:239], v[246:247], off
	v_lshl_add_u64 v[246:247], v[246:247], 0, v[244:245]
	global_load_dwordx4 v[240:243], v[246:247], off
	v_lshl_add_u64 v[246:247], v[246:247], 0, v[244:245]
	global_load_dwordx4 v[214:217], v[246:247], off
	v_lshl_add_u64 v[246:247], v[246:247], 0, v[244:245]
	global_load_dwordx4 v[218:221], v[246:247], off
	v_lshl_add_u64 v[246:247], v[246:247], 0, v[244:245]
	global_load_dwordx4 v[236:239], v[246:247], off
	v_lshl_add_u64 v[246:247], v[246:247], 0, v[244:245]
	global_load_dwordx4 v[240:243], v[246:247], off
	v_lshl_add_u64 v[246:247], v[246:247], 0, v[244:245]
	global_load_dwordx4 v[214:217], v[246:247], off
	v_lshl_add_u64 v[246:247], v[246:247], 0, v[244:245]
	global_load_dwordx4 v[218:221], v[246:247], off
	v_lshl_add_u64 v[246:247], v[246:247], 0, v[244:245]
	global_load_dwordx4 v[236:239], v[246:247], off
	v_lshl_add_u64 v[246:247], v[246:247], 0, v[244:245]
	global_load_dwordx4 v[240:243], v[246:247], off
	v_mov_b32_e32 v23, s1
	ds_read_b128 v[32:35], v23
	ds_read_b128 v[42:45], v23 offset:16
	ds_read_b128 v[46:49], v23 offset:32
	s_waitcnt vmcnt(1)
	ds_read_b128 v[14:17], v23 offset:48
	ds_read_b128 v[50:53], v23 offset:256
	ds_read_b128 v[54:57], v23 offset:512
	s_mov_b32 s22, 0x1e000
	s_add_u32 s28, s28, 0x60000
	s_addc_u32 s29, s29, 0
	s_add_i32 s1, s1, 64
	s_cmp_eq_u32 s28, 0x180000
	s_waitcnt vmcnt(0) lgkmcnt(5)
	v_pk_fma_f32 v[10:11], v[32:33], v[28:29], v[10:11] op_sel_hi:[0,1,1]
	s_waitcnt lgkmcnt(1)
	v_pk_fma_f32 v[6:7], v[28:29], v[50:51], v[6:7] op_sel_hi:[1,0,1]
	s_waitcnt lgkmcnt(0)
	v_pk_fma_f32 v[28:29], v[28:29], v[54:55], v[2:3] op_sel_hi:[1,0,1]
	v_add_co_u32_e32 v2, vcc, s45, v26
	v_pk_fma_f32 v[12:13], v[32:33], v[30:31], v[12:13] op_sel_hi:[0,1,1]
	s_nop 0
	v_addc_co_u32_e32 v3, vcc, 0, v27, vcc
	v_pk_fma_f32 v[8:9], v[30:31], v[50:51], v[8:9] op_sel_hi:[1,0,1]
	v_pk_fma_f32 v[30:31], v[30:31], v[54:55], v[4:5] op_sel_hi:[1,0,1]
	global_load_dwordx4 v[2:5], v[2:3], off nt
	s_waitcnt vmcnt(0)
	v_pk_fma_f32 v[10:11], v[32:33], v[2:3], v[10:11] op_sel:[1,0,0]
	v_pk_fma_f32 v[6:7], v[2:3], v[50:51], v[6:7] op_sel:[0,1,0]
	v_pk_fma_f32 v[28:29], v[2:3], v[54:55], v[28:29] op_sel:[0,1,0]
	v_add_co_u32_e32 v2, vcc, s36, v26
	v_pk_fma_f32 v[12:13], v[32:33], v[4:5], v[12:13] op_sel:[1,0,0]
	s_nop 0
	v_addc_co_u32_e32 v3, vcc, 0, v27, vcc
	v_pk_fma_f32 v[8:9], v[4:5], v[50:51], v[8:9] op_sel:[0,1,0]
	v_pk_fma_f32 v[30:31], v[4:5], v[54:55], v[30:31] op_sel:[0,1,0]
	global_load_dwordx4 v[2:5], v[2:3], off nt
	v_mov_b32_e32 v32, v35
	s_waitcnt vmcnt(0)
	v_pk_fma_f32 v[10:11], v[34:35], v[2:3], v[10:11] op_sel_hi:[0,1,1]
	v_pk_fma_f32 v[6:7], v[2:3], v[52:53], v[6:7] op_sel_hi:[1,0,1]
	v_pk_fma_f32 v[28:29], v[2:3], v[56:57], v[28:29] op_sel_hi:[1,0,1]
	v_add_co_u32_e32 v2, vcc, s44, v26
	v_pk_fma_f32 v[12:13], v[34:35], v[4:5], v[12:13] op_sel_hi:[0,1,1]
	s_nop 0
	v_addc_co_u32_e32 v3, vcc, 0, v27, vcc
	v_pk_fma_f32 v[8:9], v[4:5], v[52:53], v[8:9] op_sel_hi:[1,0,1]
	v_pk_fma_f32 v[30:31], v[4:5], v[56:57], v[30:31] op_sel_hi:[1,0,1]
	global_load_dwordx4 v[2:5], v[2:3], off nt
	s_waitcnt vmcnt(0)
	v_pk_fma_f32 v[34:35], v[32:33], v[2:3], v[10:11] op_sel_hi:[0,1,1]
	v_mov_b32_e32 v10, v53
	v_pk_fma_f32 v[36:37], v[2:3], v[10:11], v[6:7] op_sel_hi:[1,0,1]
	v_mov_b32_e32 v6, v57
	v_pk_fma_f32 v[28:29], v[2:3], v[6:7], v[28:29] op_sel_hi:[1,0,1]
	v_add_co_u32_e32 v2, vcc, s35, v26
	v_pk_fma_f32 v[32:33], v[32:33], v[4:5], v[12:13] op_sel_hi:[0,1,1]
	s_nop 0
	v_addc_co_u32_e32 v3, vcc, 0, v27, vcc
	v_pk_fma_f32 v[50:51], v[4:5], v[10:11], v[8:9] op_sel_hi:[1,0,1]
	v_pk_fma_f32 v[30:31], v[4:5], v[6:7], v[30:31] op_sel_hi:[1,0,1]
	global_load_dwordx4 v[2:5], v[2:3], off nt
	ds_read_b128 v[6:9], v23 offset:272
	ds_read_b128 v[10:13], v23 offset:528
	s_waitcnt vmcnt(0)
	v_pk_fma_f32 v[34:35], v[42:43], v[2:3], v[34:35] op_sel_hi:[0,1,1]
	s_waitcnt lgkmcnt(1)
	v_pk_fma_f32 v[36:37], v[2:3], v[6:7], v[36:37] op_sel_hi:[1,0,1]
	s_waitcnt lgkmcnt(0)
	v_pk_fma_f32 v[28:29], v[2:3], v[10:11], v[28:29] op_sel_hi:[1,0,1]
	v_add_co_u32_e32 v2, vcc, s22, v26
	v_pk_fma_f32 v[32:33], v[42:43], v[4:5], v[32:33] op_sel_hi:[0,1,1]
	s_nop 0
	v_addc_co_u32_e32 v3, vcc, 0, v27, vcc
	v_pk_fma_f32 v[50:51], v[4:5], v[6:7], v[50:51] op_sel_hi:[1,0,1]
	v_pk_fma_f32 v[30:31], v[4:5], v[10:11], v[30:31] op_sel_hi:[1,0,1]
	global_load_dwordx4 v[2:5], v[2:3], off nt
	s_mov_b32 s22, 0x2a000
	s_waitcnt vmcnt(0)
	v_pk_fma_f32 v[34:35], v[42:43], v[2:3], v[34:35] op_sel:[1,0,0]
	v_pk_fma_f32 v[36:37], v[2:3], v[6:7], v[36:37] op_sel:[0,1,0]
	v_pk_fma_f32 v[28:29], v[2:3], v[10:11], v[28:29] op_sel:[0,1,0]
	v_add_co_u32_e32 v2, vcc, s51, v26
	v_pk_fma_f32 v[32:33], v[42:43], v[4:5], v[32:33] op_sel:[1,0,0]
	s_nop 0
	v_addc_co_u32_e32 v3, vcc, 0, v27, vcc
	v_pk_fma_f32 v[6:7], v[4:5], v[6:7], v[50:51] op_sel:[0,1,0]
	v_pk_fma_f32 v[10:11], v[4:5], v[10:11], v[30:31] op_sel:[0,1,0]
	global_load_dwordx4 v[2:5], v[2:3], off nt
	s_waitcnt vmcnt(0)
	v_pk_fma_f32 v[30:31], v[44:45], v[2:3], v[34:35] op_sel_hi:[0,1,1]
	v_pk_fma_f32 v[34:35], v[2:3], v[8:9], v[36:37] op_sel_hi:[1,0,1]
	v_pk_fma_f32 v[28:29], v[2:3], v[12:13], v[28:29] op_sel_hi:[1,0,1]
	v_add_co_u32_e32 v2, vcc, s22, v26
	v_pk_fma_f32 v[32:33], v[44:45], v[4:5], v[32:33] op_sel_hi:[0,1,1]
	s_nop 0
	v_addc_co_u32_e32 v3, vcc, 0, v27, vcc
	v_pk_fma_f32 v[6:7], v[4:5], v[8:9], v[6:7] op_sel_hi:[1,0,1]
	v_pk_fma_f32 v[10:11], v[4:5], v[12:13], v[10:11] op_sel_hi:[1,0,1]
	global_load_dwordx4 v[2:5], v[2:3], off nt
	v_mov_b32_e32 v8, v45
	s_mov_b32 s22, 0x36000
	s_waitcnt vmcnt(0)
	v_pk_fma_f32 v[30:31], v[8:9], v[2:3], v[30:31] op_sel_hi:[0,1,1]
	v_pk_fma_f32 v[32:33], v[8:9], v[4:5], v[32:33] op_sel_hi:[0,1,1]
	v_mov_b32_e32 v8, v9
	v_pk_fma_f32 v[36:37], v[4:5], v[8:9], v[6:7] op_sel_hi:[1,0,1]
	v_mov_b32_e32 v6, v13
	v_pk_fma_f32 v[34:35], v[2:3], v[8:9], v[34:35] op_sel_hi:[1,0,1]
	v_pk_fma_f32 v[28:29], v[2:3], v[6:7], v[28:29] op_sel_hi:[1,0,1]
	v_add_co_u32_e32 v2, vcc, s52, v26
	v_pk_fma_f32 v[42:43], v[4:5], v[6:7], v[10:11] op_sel_hi:[1,0,1]
	s_nop 0
	v_addc_co_u32_e32 v3, vcc, 0, v27, vcc
	global_load_dwordx4 v[2:5], v[2:3], off nt
	ds_read_b128 v[6:9], v23 offset:288
	ds_read_b128 v[10:13], v23 offset:544
	s_waitcnt vmcnt(0)
	v_pk_fma_f32 v[30:31], v[46:47], v[2:3], v[30:31] op_sel_hi:[0,1,1]
	s_waitcnt lgkmcnt(1)
	v_pk_fma_f32 v[34:35], v[2:3], v[6:7], v[34:35] op_sel_hi:[1,0,1]
	s_waitcnt lgkmcnt(0)
	v_pk_fma_f32 v[28:29], v[2:3], v[10:11], v[28:29] op_sel_hi:[1,0,1]
	v_add_co_u32_e32 v2, vcc, s22, v26
	v_pk_fma_f32 v[32:33], v[46:47], v[4:5], v[32:33] op_sel_hi:[0,1,1]
	s_nop 0
	v_addc_co_u32_e32 v3, vcc, 0, v27, vcc
	v_pk_fma_f32 v[36:37], v[4:5], v[6:7], v[36:37] op_sel_hi:[1,0,1]
	v_pk_fma_f32 v[42:43], v[4:5], v[10:11], v[42:43] op_sel_hi:[1,0,1]
	global_load_dwordx4 v[2:5], v[2:3], off nt
	s_mov_b32 s22, 0x5a000
	s_waitcnt vmcnt(0)
	v_pk_fma_f32 v[30:31], v[46:47], v[2:3], v[30:31] op_sel:[1,0,0]
	v_pk_fma_f32 v[34:35], v[2:3], v[6:7], v[34:35] op_sel:[0,1,0]
	v_pk_fma_f32 v[28:29], v[2:3], v[10:11], v[28:29] op_sel:[0,1,0]
	v_add_co_u32_e32 v2, vcc, s96, v26
	v_pk_fma_f32 v[32:33], v[46:47], v[4:5], v[32:33] op_sel:[1,0,0]
	s_nop 0
	v_addc_co_u32_e32 v3, vcc, 0, v27, vcc
	v_pk_fma_f32 v[6:7], v[4:5], v[6:7], v[36:37] op_sel:[0,1,0]
	v_pk_fma_f32 v[10:11], v[4:5], v[10:11], v[42:43] op_sel:[0,1,0]
	global_load_dwordx4 v[2:5], v[2:3], off nt
	s_waitcnt vmcnt(0)
	v_pk_fma_f32 v[30:31], v[48:49], v[2:3], v[30:31] op_sel_hi:[0,1,1]
	v_pk_fma_f32 v[34:35], v[2:3], v[8:9], v[34:35] op_sel_hi:[1,0,1]
	v_pk_fma_f32 v[28:29], v[2:3], v[12:13], v[28:29] op_sel_hi:[1,0,1]
	v_add_co_u32_e32 v2, vcc, s38, v26
	v_pk_fma_f32 v[32:33], v[48:49], v[4:5], v[32:33] op_sel_hi:[0,1,1]
	s_nop 0
	v_addc_co_u32_e32 v3, vcc, 0, v27, vcc
	v_pk_fma_f32 v[6:7], v[4:5], v[8:9], v[6:7] op_sel_hi:[1,0,1]
	v_pk_fma_f32 v[10:11], v[4:5], v[12:13], v[10:11] op_sel_hi:[1,0,1]
	global_load_dwordx4 v[2:5], v[2:3], off nt
	v_mov_b32_e32 v8, v49
	s_waitcnt vmcnt(0)
	v_pk_fma_f32 v[36:37], v[8:9], v[2:3], v[30:31] op_sel_hi:[0,1,1]
	v_pk_fma_f32 v[32:33], v[8:9], v[4:5], v[32:33] op_sel_hi:[0,1,1]
	v_mov_b32_e32 v8, v9
	v_pk_fma_f32 v[42:43], v[4:5], v[8:9], v[6:7] op_sel_hi:[1,0,1]
	v_mov_b32_e32 v6, v13
	v_pk_fma_f32 v[34:35], v[2:3], v[8:9], v[34:35] op_sel_hi:[1,0,1]
	v_pk_fma_f32 v[12:13], v[2:3], v[6:7], v[28:29] op_sel_hi:[1,0,1]
	v_add_co_u32_e32 v2, vcc, s46, v26
	v_pk_fma_f32 v[10:11], v[4:5], v[6:7], v[10:11] op_sel_hi:[1,0,1]
	s_nop 0
	v_addc_co_u32_e32 v3, vcc, 0, v27, vcc
	global_load_dwordx4 v[2:5], v[2:3], off nt
	ds_read_b128 v[6:9], v23 offset:304
	ds_read_b128 v[28:31], v23 offset:560
	s_waitcnt vmcnt(0)
	v_pk_fma_f32 v[36:37], v[14:15], v[2:3], v[36:37] op_sel_hi:[0,1,1]
	s_waitcnt lgkmcnt(1)
	v_pk_fma_f32 v[34:35], v[2:3], v[6:7], v[34:35] op_sel_hi:[1,0,1]
	s_waitcnt lgkmcnt(0)
	v_pk_fma_f32 v[12:13], v[2:3], v[28:29], v[12:13] op_sel_hi:[1,0,1]
	v_add_co_u32_e32 v2, vcc, s53, v26
	v_pk_fma_f32 v[32:33], v[14:15], v[4:5], v[32:33] op_sel_hi:[0,1,1]
	s_nop 0
	v_addc_co_u32_e32 v3, vcc, 0, v27, vcc
	v_pk_fma_f32 v[42:43], v[4:5], v[6:7], v[42:43] op_sel_hi:[1,0,1]
	v_pk_fma_f32 v[10:11], v[4:5], v[28:29], v[10:11] op_sel_hi:[1,0,1]
	global_load_dwordx4 v[2:5], v[2:3], off nt
	s_waitcnt vmcnt(0)
	v_pk_fma_f32 v[36:37], v[14:15], v[2:3], v[36:37] op_sel:[1,0,0]
	v_pk_fma_f32 v[14:15], v[14:15], v[4:5], v[32:33] op_sel:[1,0,0]
	v_pk_fma_f32 v[32:33], v[2:3], v[6:7], v[34:35] op_sel:[0,1,0]
	v_pk_fma_f32 v[12:13], v[2:3], v[28:29], v[12:13] op_sel:[0,1,0]
	v_add_co_u32_e32 v2, vcc, s97, v26
	v_pk_fma_f32 v[6:7], v[4:5], v[6:7], v[42:43] op_sel:[0,1,0]
	s_nop 0
	v_addc_co_u32_e32 v3, vcc, 0, v27, vcc
	v_pk_fma_f32 v[10:11], v[4:5], v[28:29], v[10:11] op_sel:[0,1,0]
	global_load_dwordx4 v[2:5], v[2:3], off nt
	s_waitcnt vmcnt(0)
	v_pk_fma_f32 v[28:29], v[16:17], v[2:3], v[36:37] op_sel_hi:[0,1,1]
	v_pk_fma_f32 v[32:33], v[2:3], v[8:9], v[32:33] op_sel_hi:[1,0,1]
	v_pk_fma_f32 v[36:37], v[2:3], v[30:31], v[12:13] op_sel_hi:[1,0,1]
	v_add_co_u32_e32 v2, vcc, s22, v26
	v_pk_fma_f32 v[14:15], v[16:17], v[4:5], v[14:15] op_sel_hi:[0,1,1]
	s_nop 0
	v_addc_co_u32_e32 v3, vcc, 0, v27, vcc
	v_pk_fma_f32 v[34:35], v[4:5], v[8:9], v[6:7] op_sel_hi:[1,0,1]
	v_pk_fma_f32 v[42:43], v[4:5], v[30:31], v[10:11] op_sel_hi:[1,0,1]
	global_load_dwordx4 v[2:5], v[2:3], off nt
	v_mov_b32_e32 v6, v17
	v_mov_b32_e32 v8, v9
	s_waitcnt vmcnt(0)
	v_pk_fma_f32 v[12:13], v[6:7], v[4:5], v[14:15] op_sel_hi:[0,1,1]
	v_mov_b32_e32 v14, v31
	v_pk_fma_f32 v[10:11], v[6:7], v[2:3], v[28:29] op_sel_hi:[0,1,1]
	v_pk_fma_f32 v[6:7], v[2:3], v[8:9], v[32:33] op_sel_hi:[1,0,1]
	v_pk_fma_f32 v[8:9], v[4:5], v[8:9], v[34:35] op_sel_hi:[1,0,1]
	v_pk_fma_f32 v[2:3], v[2:3], v[14:15], v[36:37] op_sel_hi:[1,0,1]
	v_pk_fma_f32 v[4:5], v[4:5], v[14:15], v[42:43] op_sel_hi:[1,0,1]
	s_cbranch_scc0 .LBB0_1022
	s_lshl_b32 s1, s21, 2
	s_add_i32 s0, s1, s0
	v_readlane_b32 s4, v254, 0
	s_mul_i32 s1, s0, 3
	s_mul_i32 s0, s0, 0x12000
	v_readlane_b32 s8, v254, 4
	s_mul_hi_i32 s1, s1, 0x6000
	v_readlane_b32 s9, v254, 5
	s_add_u32 s0, s8, s0
	v_lshlrev_b32_e32 v14, 2, v22
	s_addc_u32 s1, s9, s1
	v_ashrrev_i32_e32 v15, 31, v14
	v_lshl_add_u64 v[14:15], v[14:15], 2, s[0:1]
	global_store_dwordx4 v[14:15], v[10:13], off
	s_mov_b32 s0, s34
	v_readlane_b32 s5, v254, 1
	v_add_co_u32_e32 v10, vcc, s45, v14
	v_readlane_b32 s6, v254, 2
	s_nop 0
	v_addc_co_u32_e32 v11, vcc, 0, v15, vcc
	global_store_dwordx4 v[10:11], v[6:9], off
	v_readlane_b32 s7, v254, 3
	v_readlane_b32 s10, v254, 6
	v_add_co_u32_e32 v6, vcc, 0xc000, v14
	v_readlane_b32 s11, v254, 7
	s_nop 0
	v_addc_co_u32_e32 v7, vcc, 0, v15, vcc
	global_store_dwordx4 v[6:7], v[2:5], off
	s_barrier
	s_lshl_b32 s0, s0, 1
	s_add_i32 s20, s0, s20
	s_cmpk_gt_i32 s20, 0x17f
	v_readlane_b32 s12, v254, 8
	v_readlane_b32 s13, v254, 9
	v_readlane_b32 s14, v254, 10
	v_readlane_b32 s15, v254, 11
	v_readlane_b32 s16, v254, 12
	v_readlane_b32 s17, v254, 13
	v_readlane_b32 s18, v254, 14
	v_readlane_b32 s19, v254, 15
	s_cbranch_scc0 .LBB0_1019
